# v97 minus the lgkmcnt(8) pre-barrier waits in the 5 full GEMM K-loops (reads are covered by the later lgkmcnt(0))
# speedup vs baseline: 1.0017x; 1.0017x over previous
.LBB0_34:
	ds_read_b128 v[164:167], v151
	ds_read_b128 v[168:171], v151 offset:1024
	ds_read_b128 v[172:175], v151 offset:2048
	ds_read_b128 v[176:179], v151 offset:3072
	v_lshl_add_u64 v[204:205], v[138:139], 0, s[12:13]
	v_lshl_add_u64 v[228:229], v[204:205], 0, s[60:61]
	s_add_i32 m0, s1, 0xc000
	ds_read_b128 v[180:183], v0
	ds_read_b128 v[184:187], v0 offset:1024
	ds_read_b128 v[188:191], v0 offset:2048
	ds_read_b128 v[192:195], v0 offset:3072
	ds_read_b128 v[196:199], v0 offset:4096
	ds_read_b128 v[200:203], v0 offset:5120
	ds_read_b128 v[222:225], v0 offset:6144
	ds_read_b128 v[232:235], v0 offset:7168
	global_load_lds_dwordx4 v[228:229], off
	v_lshl_add_u64 v[210:211], v[140:141], 0, s[12:13]
	s_add_i32 m0, s1, 0xe000
	v_lshl_add_u64 v[152:153], v[210:211], 0, s[60:61]
	global_load_lds_dwordx4 v[152:153], off
	s_barrier
	s_waitcnt lgkmcnt(0)
	v_mfma_f32_16x16x32_bf16 v[126:129], v[164:167], v[180:183], v[126:129]
	v_mfma_f32_16x16x32_bf16 v[122:125], v[172:175], v[180:183], v[122:125]
	v_mfma_f32_16x16x32_bf16 v[118:121], v[164:167], v[188:191], v[118:121]
	v_mfma_f32_16x16x32_bf16 v[114:117], v[172:175], v[188:191], v[114:117]
	v_mfma_f32_16x16x32_bf16 v[110:113], v[164:167], v[196:199], v[110:113]
	v_mfma_f32_16x16x32_bf16 v[106:109], v[172:175], v[196:199], v[106:109]
	v_mfma_f32_16x16x32_bf16 v[102:105], v[164:167], v[222:225], v[102:105]
	v_mfma_f32_16x16x32_bf16 v[98:101], v[172:175], v[222:225], v[98:101]
	v_mfma_f32_16x16x32_bf16 v[126:129], v[168:171], v[184:187], v[126:129]
	v_mfma_f32_16x16x32_bf16 v[122:125], v[176:179], v[184:187], v[122:125]
	v_mfma_f32_16x16x32_bf16 v[118:121], v[168:171], v[192:195], v[118:121]
	v_mfma_f32_16x16x32_bf16 v[114:117], v[176:179], v[192:195], v[114:117]
	v_mfma_f32_16x16x32_bf16 v[110:113], v[168:171], v[200:203], v[110:113]
	v_mfma_f32_16x16x32_bf16 v[106:109], v[176:179], v[200:203], v[106:109]
	v_mfma_f32_16x16x32_bf16 v[102:105], v[168:171], v[232:235], v[102:105]
	v_mfma_f32_16x16x32_bf16 v[98:101], v[176:179], v[232:235], v[98:101]
	s_barrier
	v_lshl_add_u64 v[216:217], v[134:135], 0, s[12:13]
	s_add_i32 m0, s1, 0xff00
	ds_read_b128 v[236:239], v151 offset:16384
	ds_read_b128 v[240:243], v151 offset:17408
	ds_read_b128 v[244:247], v151 offset:18432
	ds_read_b128 v[248:251], v151 offset:19456
	global_load_lds_dwordx4 v[216:217], off offset:256
	s_add_i32 m0, s1, 0x11f00
	v_lshl_add_u64 v[218:219], v[136:137], 0, s[12:13]
	global_load_lds_dwordx4 v[218:219], off offset:256
	s_barrier
	s_waitcnt lgkmcnt(0)
	v_mfma_f32_16x16x32_bf16 v[94:97], v[236:239], v[180:183], v[94:97]
	v_mfma_f32_16x16x32_bf16 v[90:93], v[244:247], v[180:183], v[90:93]
	v_mfma_f32_16x16x32_bf16 v[86:89], v[236:239], v[188:191], v[86:89]
	v_mfma_f32_16x16x32_bf16 v[70:73], v[244:247], v[188:191], v[70:73]
	v_mfma_f32_16x16x32_bf16 v[62:65], v[236:239], v[196:199], v[62:65]
	v_mfma_f32_16x16x32_bf16 v[58:61], v[244:247], v[196:199], v[58:61]
	v_mfma_f32_16x16x32_bf16 v[54:57], v[236:239], v[222:225], v[54:57]
	v_mfma_f32_16x16x32_bf16 v[50:53], v[244:247], v[222:225], v[50:53]
	v_mfma_f32_16x16x32_bf16 v[94:97], v[240:243], v[184:187], v[94:97]
	v_mfma_f32_16x16x32_bf16 v[90:93], v[248:251], v[184:187], v[90:93]
	v_mfma_f32_16x16x32_bf16 v[86:89], v[240:243], v[192:195], v[86:89]
	v_mfma_f32_16x16x32_bf16 v[70:73], v[248:251], v[192:195], v[70:73]
	v_mfma_f32_16x16x32_bf16 v[62:65], v[240:243], v[200:203], v[62:65]
	v_mfma_f32_16x16x32_bf16 v[58:61], v[248:251], v[200:203], v[58:61]
	v_mfma_f32_16x16x32_bf16 v[54:57], v[240:243], v[232:235], v[54:57]
	v_mfma_f32_16x16x32_bf16 v[50:53], v[248:251], v[232:235], v[50:53]
	v_lshl_add_u64 v[158:159], v[204:205], 0, s[74:75]
	s_mov_b32 m0, s1
	s_barrier
	ds_read_b128 v[180:183], v0 offset:16384
	ds_read_b128 v[184:187], v0 offset:17408
	ds_read_b128 v[188:191], v0 offset:18432
	ds_read_b128 v[192:195], v0 offset:19456
	ds_read_b128 v[196:199], v0 offset:20480
	ds_read_b128 v[200:203], v0 offset:21504
	ds_read_b128 v[222:225], v0 offset:22528
	ds_read_b128 v[232:235], v0 offset:23552
	global_load_lds_dwordx4 v[158:159], off
	s_add_i32 m0, s1, 0x1f00
	s_nop 0
	global_load_lds_dwordx4 v[210:211], off offset:256
	s_barrier
	s_waitcnt lgkmcnt(0)
	v_mfma_f32_16x16x32_bf16 v[46:49], v[164:167], v[180:183], v[46:49]
	v_mfma_f32_16x16x32_bf16 v[42:45], v[172:175], v[180:183], v[42:45]
	v_mfma_f32_16x16x32_bf16 v[38:41], v[164:167], v[188:191], v[38:41]
	v_mfma_f32_16x16x32_bf16 v[34:37], v[172:175], v[188:191], v[34:37]
	v_mfma_f32_16x16x32_bf16 v[30:33], v[164:167], v[196:199], v[30:33]
	v_mfma_f32_16x16x32_bf16 v[26:29], v[172:175], v[196:199], v[26:29]
	v_mfma_f32_16x16x32_bf16 v[22:25], v[164:167], v[222:225], v[22:25]
	v_mfma_f32_16x16x32_bf16 v[18:21], v[172:175], v[222:225], v[18:21]
	v_mfma_f32_16x16x32_bf16 v[46:49], v[168:171], v[184:187], v[46:49]
	v_mfma_f32_16x16x32_bf16 v[42:45], v[176:179], v[184:187], v[42:45]
	v_mfma_f32_16x16x32_bf16 v[38:41], v[168:171], v[192:195], v[38:41]
	v_mfma_f32_16x16x32_bf16 v[34:37], v[176:179], v[192:195], v[34:37]
	v_mfma_f32_16x16x32_bf16 v[30:33], v[168:171], v[200:203], v[30:33]
	v_mfma_f32_16x16x32_bf16 v[26:29], v[176:179], v[200:203], v[26:29]
	v_mfma_f32_16x16x32_bf16 v[22:25], v[168:171], v[232:235], v[22:25]
	v_mfma_f32_16x16x32_bf16 v[18:21], v[176:179], v[232:235], v[18:21]
	s_barrier
	s_add_i32 m0, s1, 0x14000
	v_lshl_add_u64 v[154:155], v[216:217], 0, s[18:19]
	global_load_lds_dwordx4 v[154:155], off
	s_add_i32 m0, s1, 0x16000
	v_lshl_add_u64 v[156:157], v[218:219], 0, s[18:19]
	global_load_lds_dwordx4 v[156:157], off
	s_waitcnt vmcnt(6)
	s_barrier
	v_mfma_f32_16x16x32_bf16 v[14:17], v[236:239], v[180:183], v[14:17]
	v_mfma_f32_16x16x32_bf16 v[10:13], v[244:247], v[180:183], v[10:13]
	v_mfma_f32_16x16x32_bf16 v[6:9], v[236:239], v[188:191], v[6:9]
	v_mfma_f32_16x16x32_bf16 v[2:5], v[244:247], v[188:191], v[2:5]
	v_mfma_f32_16x16x32_bf16 v[66:69], v[236:239], v[196:199], v[66:69]
	v_mfma_f32_16x16x32_bf16 v[74:77], v[244:247], v[196:199], v[74:77]
	v_mfma_f32_16x16x32_bf16 v[78:81], v[236:239], v[222:225], v[78:81]
	v_mfma_f32_16x16x32_bf16 v[82:85], v[244:247], v[222:225], v[82:85]
	v_mfma_f32_16x16x32_bf16 v[14:17], v[240:243], v[184:187], v[14:17]
	v_mfma_f32_16x16x32_bf16 v[10:13], v[248:251], v[184:187], v[10:13]
	v_mfma_f32_16x16x32_bf16 v[6:9], v[240:243], v[192:195], v[6:9]
	v_mfma_f32_16x16x32_bf16 v[2:5], v[248:251], v[192:195], v[2:5]
	v_mfma_f32_16x16x32_bf16 v[66:69], v[240:243], v[200:203], v[66:69]
	v_mfma_f32_16x16x32_bf16 v[74:77], v[248:251], v[200:203], v[74:77]
	v_mfma_f32_16x16x32_bf16 v[78:81], v[240:243], v[232:235], v[78:81]
	v_mfma_f32_16x16x32_bf16 v[82:85], v[248:251], v[232:235], v[82:85]
	s_barrier
	ds_read_b128 v[164:167], v151 offset:32768
	ds_read_b128 v[168:171], v151 offset:33792
	ds_read_b128 v[172:175], v151 offset:34816
	ds_read_b128 v[176:179], v151 offset:35840
	s_add_i32 m0, s1, 0x3f80
	ds_read_b128 v[180:183], v0 offset:32768
	ds_read_b128 v[184:187], v0 offset:33792
	ds_read_b128 v[188:191], v0 offset:34816
	ds_read_b128 v[192:195], v0 offset:35840
	ds_read_b128 v[196:199], v0 offset:36864
	ds_read_b128 v[200:203], v0 offset:37888
	ds_read_b128 v[222:225], v0 offset:38912
	ds_read_b128 v[232:235], v0 offset:39936
	global_load_lds_dwordx4 v[228:229], off offset:128
	s_add_i32 m0, s1, 0x5f80
	s_nop 0
	global_load_lds_dwordx4 v[152:153], off offset:128
	s_barrier
	s_waitcnt lgkmcnt(0)
	v_mfma_f32_16x16x32_bf16 v[126:129], v[164:167], v[180:183], v[126:129]
	v_mfma_f32_16x16x32_bf16 v[122:125], v[172:175], v[180:183], v[122:125]
	v_mfma_f32_16x16x32_bf16 v[118:121], v[164:167], v[188:191], v[118:121]
	v_mfma_f32_16x16x32_bf16 v[114:117], v[172:175], v[188:191], v[114:117]
	v_mfma_f32_16x16x32_bf16 v[110:113], v[164:167], v[196:199], v[110:113]
	v_mfma_f32_16x16x32_bf16 v[106:109], v[172:175], v[196:199], v[106:109]
	v_mfma_f32_16x16x32_bf16 v[102:105], v[164:167], v[222:225], v[102:105]
	v_mfma_f32_16x16x32_bf16 v[98:101], v[172:175], v[222:225], v[98:101]
	v_mfma_f32_16x16x32_bf16 v[126:129], v[168:171], v[184:187], v[126:129]
	v_mfma_f32_16x16x32_bf16 v[122:125], v[176:179], v[184:187], v[122:125]
	v_mfma_f32_16x16x32_bf16 v[118:121], v[168:171], v[192:195], v[118:121]
	v_mfma_f32_16x16x32_bf16 v[114:117], v[176:179], v[192:195], v[114:117]
	v_mfma_f32_16x16x32_bf16 v[110:113], v[168:171], v[200:203], v[110:113]
	v_mfma_f32_16x16x32_bf16 v[106:109], v[176:179], v[200:203], v[106:109]
	v_mfma_f32_16x16x32_bf16 v[102:105], v[168:171], v[232:235], v[102:105]
	v_mfma_f32_16x16x32_bf16 v[98:101], v[176:179], v[232:235], v[98:101]
	s_barrier
	s_add_i32 m0, s1, 0x17e80
	ds_read_b128 v[236:239], v151 offset:49152
	ds_read_b128 v[240:243], v151 offset:50176
	ds_read_b128 v[244:247], v151 offset:51200
	ds_read_b128 v[248:251], v151 offset:52224
	global_load_lds_dwordx4 v[216:217], off offset:384
	s_add_i32 m0, s1, 0x19e80
	s_nop 0
	global_load_lds_dwordx4 v[218:219], off offset:384
	s_barrier
	s_waitcnt lgkmcnt(0)
	v_mfma_f32_16x16x32_bf16 v[94:97], v[236:239], v[180:183], v[94:97]
	v_mfma_f32_16x16x32_bf16 v[90:93], v[244:247], v[180:183], v[90:93]
	v_mfma_f32_16x16x32_bf16 v[86:89], v[236:239], v[188:191], v[86:89]
	v_mfma_f32_16x16x32_bf16 v[70:73], v[244:247], v[188:191], v[70:73]
	v_mfma_f32_16x16x32_bf16 v[62:65], v[236:239], v[196:199], v[62:65]
	v_mfma_f32_16x16x32_bf16 v[58:61], v[244:247], v[196:199], v[58:61]
	v_mfma_f32_16x16x32_bf16 v[54:57], v[236:239], v[222:225], v[54:57]
	v_mfma_f32_16x16x32_bf16 v[50:53], v[244:247], v[222:225], v[50:53]
	v_mfma_f32_16x16x32_bf16 v[94:97], v[240:243], v[184:187], v[94:97]
	v_mfma_f32_16x16x32_bf16 v[90:93], v[248:251], v[184:187], v[90:93]
	v_mfma_f32_16x16x32_bf16 v[86:89], v[240:243], v[192:195], v[86:89]
	v_mfma_f32_16x16x32_bf16 v[70:73], v[248:251], v[192:195], v[70:73]
	v_mfma_f32_16x16x32_bf16 v[62:65], v[240:243], v[200:203], v[62:65]
	v_mfma_f32_16x16x32_bf16 v[58:61], v[248:251], v[200:203], v[58:61]
	v_mfma_f32_16x16x32_bf16 v[54:57], v[240:243], v[232:235], v[54:57]
	v_mfma_f32_16x16x32_bf16 v[50:53], v[248:251], v[232:235], v[50:53]
	s_add_i32 m0, s1, 0x7e80
	s_barrier
	ds_read_b128 v[180:183], v0 offset:49152
	ds_read_b128 v[184:187], v0 offset:50176
	ds_read_b128 v[188:191], v0 offset:51200
	ds_read_b128 v[192:195], v0 offset:52224
	ds_read_b128 v[196:199], v0 offset:53248
	ds_read_b128 v[200:203], v0 offset:54272
	ds_read_b128 v[222:225], v0 offset:55296
	ds_read_b128 v[232:235], v0 offset:56320
	global_load_lds_dwordx4 v[204:205], off offset:384
	s_add_i32 m0, s1, 0x9e80
	s_nop 0
	global_load_lds_dwordx4 v[210:211], off offset:384
	s_barrier
	s_waitcnt lgkmcnt(0)
	v_mfma_f32_16x16x32_bf16 v[46:49], v[164:167], v[180:183], v[46:49]
	v_mfma_f32_16x16x32_bf16 v[42:45], v[172:175], v[180:183], v[42:45]
	v_mfma_f32_16x16x32_bf16 v[38:41], v[164:167], v[188:191], v[38:41]
	v_mfma_f32_16x16x32_bf16 v[34:37], v[172:175], v[188:191], v[34:37]
	v_mfma_f32_16x16x32_bf16 v[30:33], v[164:167], v[196:199], v[30:33]
	v_mfma_f32_16x16x32_bf16 v[26:29], v[172:175], v[196:199], v[26:29]
	v_mfma_f32_16x16x32_bf16 v[22:25], v[164:167], v[222:225], v[22:25]
	v_mfma_f32_16x16x32_bf16 v[18:21], v[172:175], v[222:225], v[18:21]
	v_mfma_f32_16x16x32_bf16 v[46:49], v[168:171], v[184:187], v[46:49]
	v_mfma_f32_16x16x32_bf16 v[42:45], v[176:179], v[184:187], v[42:45]
	v_mfma_f32_16x16x32_bf16 v[38:41], v[168:171], v[192:195], v[38:41]
	v_mfma_f32_16x16x32_bf16 v[34:37], v[176:179], v[192:195], v[34:37]
	v_mfma_f32_16x16x32_bf16 v[30:33], v[168:171], v[200:203], v[30:33]
	v_mfma_f32_16x16x32_bf16 v[26:29], v[176:179], v[200:203], v[26:29]
	v_mfma_f32_16x16x32_bf16 v[22:25], v[168:171], v[232:235], v[22:25]
	v_mfma_f32_16x16x32_bf16 v[18:21], v[176:179], v[232:235], v[18:21]
	s_barrier
	s_add_i32 m0, s1, 0x1bf80
	s_nop 0
	global_load_lds_dwordx4 v[154:155], off offset:128
	s_add_i32 m0, s1, 0x1df80
	s_nop 0
	global_load_lds_dwordx4 v[156:157], off offset:128
	s_waitcnt vmcnt(6)
	s_barrier
	v_mfma_f32_16x16x32_bf16 v[14:17], v[236:239], v[180:183], v[14:17]
	v_mfma_f32_16x16x32_bf16 v[10:13], v[244:247], v[180:183], v[10:13]
	v_mfma_f32_16x16x32_bf16 v[6:9], v[236:239], v[188:191], v[6:9]
	v_mfma_f32_16x16x32_bf16 v[2:5], v[244:247], v[188:191], v[2:5]
	v_mfma_f32_16x16x32_bf16 v[66:69], v[236:239], v[196:199], v[66:69]
	v_mfma_f32_16x16x32_bf16 v[74:77], v[244:247], v[196:199], v[74:77]
	v_mfma_f32_16x16x32_bf16 v[78:81], v[236:239], v[222:225], v[78:81]
	v_mfma_f32_16x16x32_bf16 v[82:85], v[244:247], v[222:225], v[82:85]
	v_mfma_f32_16x16x32_bf16 v[14:17], v[240:243], v[184:187], v[14:17]
	v_mfma_f32_16x16x32_bf16 v[10:13], v[248:251], v[184:187], v[10:13]
	v_mfma_f32_16x16x32_bf16 v[6:9], v[240:243], v[192:195], v[6:9]
	v_mfma_f32_16x16x32_bf16 v[2:5], v[248:251], v[192:195], v[2:5]
	v_mfma_f32_16x16x32_bf16 v[66:69], v[240:243], v[200:203], v[66:69]
	v_mfma_f32_16x16x32_bf16 v[74:77], v[248:251], v[200:203], v[74:77]
	v_mfma_f32_16x16x32_bf16 v[78:81], v[240:243], v[232:235], v[78:81]
	v_mfma_f32_16x16x32_bf16 v[82:85], v[248:251], v[232:235], v[82:85]
	s_add_i32 s0, s0, 2
	s_add_u32 s12, s12, 0x100
	s_addc_u32 s13, s13, 0
	s_cmp_lt_u32 s0, 28
	s_barrier
	s_cbranch_scc1 .LBB0_34
	s_add_i32 s1, s1, 0x1e000
	s_mov_b64 s[12:13], 0xf80
	v_readfirstlane_b32 s0, v162
	v_lshl_add_u64 v[132:133], v[132:133], 0, s[12:13]
	s_mov_b32 m0, s0
	v_readfirstlane_b32 s0, v163
	ds_read_b128 v[134:137], v151
	ds_read_b128 v[138:141], v151 offset:1024
	ds_read_b128 v[152:155], v151 offset:2048
	ds_read_b128 v[156:159], v151 offset:3072
	ds_read_b128 v[164:167], v0
	ds_read_b128 v[168:171], v0 offset:1024
	ds_read_b128 v[172:175], v0 offset:2048
	ds_read_b128 v[176:179], v0 offset:3072
	ds_read_b128 v[180:183], v0 offset:4096
	ds_read_b128 v[184:187], v0 offset:5120
	ds_read_b128 v[188:191], v0 offset:6144
	ds_read_b128 v[192:195], v0 offset:7168
	global_load_lds_dwordx4 v[132:133], off
	v_lshl_add_u64 v[130:131], v[130:131], 0, s[12:13]
	s_mov_b32 m0, s0
	s_nop 0
	global_load_lds_dwordx4 v[130:131], off
	s_barrier
	s_waitcnt lgkmcnt(0)
	s_setprio 1
	s_waitcnt lgkmcnt(0)
	v_mfma_f32_16x16x32_bf16 v[122:125], v[152:155], v[164:167], v[122:125]
	v_mfma_f32_16x16x32_bf16 v[118:121], v[134:137], v[172:175], v[118:121]
	v_mfma_f32_16x16x32_bf16 v[114:117], v[152:155], v[172:175], v[114:117]
	v_mfma_f32_16x16x32_bf16 v[102:105], v[134:137], v[188:191], v[102:105]
	v_mfma_f32_16x16x32_bf16 v[98:101], v[152:155], v[188:191], v[98:101]
	v_mfma_f32_16x16x32_bf16 v[126:129], v[134:137], v[164:167], v[126:129]
	v_mfma_f32_16x16x32_bf16 v[122:125], v[156:159], v[168:171], v[122:125]
	v_mfma_f32_16x16x32_bf16 v[118:121], v[138:141], v[176:179], v[118:121]
	v_mfma_f32_16x16x32_bf16 v[114:117], v[156:159], v[176:179], v[114:117]
	v_mfma_f32_16x16x32_bf16 v[110:113], v[134:137], v[180:183], v[110:113]
	v_mfma_f32_16x16x32_bf16 v[106:109], v[152:155], v[180:183], v[106:109]
	v_mfma_f32_16x16x32_bf16 v[102:105], v[138:141], v[192:195], v[102:105]
	v_mfma_f32_16x16x32_bf16 v[98:101], v[156:159], v[192:195], v[98:101]
	v_mfma_f32_16x16x32_bf16 v[126:129], v[138:141], v[168:171], v[126:129]
	v_mfma_f32_16x16x32_bf16 v[130:133], v[138:141], v[184:187], v[110:113]
	v_mfma_f32_16x16x32_bf16 v[160:163], v[156:159], v[184:187], v[106:109]
	s_setprio 0
	s_barrier
	ds_read_b128 v[106:109], v151 offset:16384
	ds_read_b128 v[110:113], v151 offset:17408
	ds_read_b128 v[196:199], v151 offset:18432
	ds_read_b128 v[200:203], v151 offset:19456
	s_barrier
	s_waitcnt lgkmcnt(0)
	s_setprio 1
	s_waitcnt lgkmcnt(3)
	v_mfma_f32_16x16x32_bf16 v[86:89], v[106:109], v[172:175], v[86:89]
	s_waitcnt lgkmcnt(1)
	v_mfma_f32_16x16x32_bf16 v[70:73], v[196:199], v[172:175], v[70:73]
	v_mfma_f32_16x16x32_bf16 v[62:65], v[106:109], v[180:183], v[62:65]
	v_mfma_f32_16x16x32_bf16 v[58:61], v[196:199], v[180:183], v[58:61]
	v_mfma_f32_16x16x32_bf16 v[54:57], v[106:109], v[188:191], v[54:57]
	v_mfma_f32_16x16x32_bf16 v[50:53], v[196:199], v[188:191], v[50:53]
	v_mfma_f32_16x16x32_bf16 v[94:97], v[106:109], v[164:167], v[94:97]
	v_mfma_f32_16x16x32_bf16 v[90:93], v[196:199], v[164:167], v[90:93]
	v_mfma_f32_16x16x32_bf16 v[86:89], v[110:113], v[176:179], v[86:89]
	s_waitcnt lgkmcnt(0)
	v_mfma_f32_16x16x32_bf16 v[70:73], v[200:203], v[176:179], v[70:73]
	v_mfma_f32_16x16x32_bf16 v[62:65], v[110:113], v[184:187], v[62:65]
	v_mfma_f32_16x16x32_bf16 v[58:61], v[200:203], v[184:187], v[58:61]
	v_mfma_f32_16x16x32_bf16 v[54:57], v[110:113], v[192:195], v[54:57]
	v_mfma_f32_16x16x32_bf16 v[50:53], v[200:203], v[192:195], v[50:53]
	v_mfma_f32_16x16x32_bf16 v[222:225], v[110:113], v[168:171], v[94:97]
	v_mfma_f32_16x16x32_bf16 v[164:167], v[200:203], v[168:171], v[90:93]
	s_setprio 0
	s_barrier
	s_nop 0
	ds_read_b128 v[90:93], v0 offset:16384
	ds_read_b128 v[94:97], v0 offset:17408
	ds_read_b128 v[168:171], v0 offset:18432
	ds_read_b128 v[172:175], v0 offset:19456
	ds_read_b128 v[176:179], v0 offset:20480
	ds_read_b128 v[180:183], v0 offset:21504
	ds_read_b128 v[184:187], v0 offset:22528
	ds_read_b128 v[188:191], v0 offset:23552
	s_waitcnt vmcnt(4)
	s_barrier
	s_waitcnt lgkmcnt(0)
	s_setprio 1
	s_waitcnt lgkmcnt(7)
	v_mfma_f32_16x16x32_bf16 v[46:49], v[134:137], v[90:93], v[46:49]
	v_mfma_f32_16x16x32_bf16 v[42:45], v[152:155], v[90:93], v[42:45]
	s_waitcnt lgkmcnt(5)
	v_mfma_f32_16x16x32_bf16 v[38:41], v[134:137], v[168:171], v[38:41]
	v_mfma_f32_16x16x32_bf16 v[34:37], v[152:155], v[168:171], v[34:37]
	s_waitcnt lgkmcnt(3)
	v_mfma_f32_16x16x32_bf16 v[30:33], v[134:137], v[176:179], v[30:33]
	v_mfma_f32_16x16x32_bf16 v[26:29], v[152:155], v[176:179], v[26:29]
	s_waitcnt lgkmcnt(1)
	v_mfma_f32_16x16x32_bf16 v[22:25], v[134:137], v[184:187], v[22:25]
	v_mfma_f32_16x16x32_bf16 v[18:21], v[152:155], v[184:187], v[18:21]
	v_mfma_f32_16x16x32_bf16 v[46:49], v[138:141], v[94:97], v[46:49]
	v_mfma_f32_16x16x32_bf16 v[42:45], v[156:159], v[94:97], v[42:45]
	v_mfma_f32_16x16x32_bf16 v[38:41], v[138:141], v[172:175], v[38:41]
	v_mfma_f32_16x16x32_bf16 v[34:37], v[156:159], v[172:175], v[34:37]
	v_mfma_f32_16x16x32_bf16 v[30:33], v[138:141], v[180:183], v[30:33]
	v_mfma_f32_16x16x32_bf16 v[26:29], v[156:159], v[180:183], v[26:29]
	s_waitcnt lgkmcnt(0)
	v_mfma_f32_16x16x32_bf16 v[22:25], v[138:141], v[188:191], v[22:25]
	v_mfma_f32_16x16x32_bf16 v[18:21], v[156:159], v[188:191], v[18:21]
	s_setprio 0
	s_setprio 1
	v_mfma_f32_16x16x32_bf16 v[10:13], v[196:199], v[90:93], v[10:13]
	v_mfma_f32_16x16x32_bf16 v[152:155], v[200:203], v[94:97], v[10:13]
	v_mfma_f32_16x16x32_bf16 v[10:13], v[106:109], v[176:179], v[66:69]
	v_mfma_f32_16x16x32_bf16 v[156:159], v[110:113], v[180:183], v[10:13]
	v_mfma_f32_16x16x32_bf16 v[10:13], v[196:199], v[176:179], v[74:77]
	v_mfma_f32_16x16x32_bf16 v[6:9], v[106:109], v[168:171], v[6:9]
	v_mfma_f32_16x16x32_bf16 v[2:5], v[196:199], v[168:171], v[2:5]
	v_mfma_f32_16x16x32_bf16 v[168:171], v[200:203], v[180:183], v[10:13]
	v_mfma_f32_16x16x32_bf16 v[10:13], v[106:109], v[184:187], v[78:81]
	v_mfma_f32_16x16x32_bf16 v[14:17], v[106:109], v[90:93], v[14:17]
	v_mfma_f32_16x16x32_bf16 v[6:9], v[110:113], v[172:175], v[6:9]
	v_mfma_f32_16x16x32_bf16 v[2:5], v[200:203], v[172:175], v[2:5]
	v_mfma_f32_16x16x32_bf16 v[172:175], v[110:113], v[188:191], v[10:13]
	v_mfma_f32_16x16x32_bf16 v[10:13], v[196:199], v[184:187], v[82:85]
	v_mfma_f32_16x16x32_bf16 v[134:137], v[110:113], v[94:97], v[14:17]
	v_mfma_f32_16x16x32_bf16 v[176:179], v[200:203], v[188:191], v[10:13]
	s_setprio 0
	s_barrier
	s_nop 3
	ds_read_b128 v[10:13], v151 offset:32768
	ds_read_b128 v[14:17], v151 offset:33792
	ds_read_b128 v[180:183], v151 offset:34816
	ds_read_b128 v[184:187], v151 offset:35840
	ds_read_b128 v[66:69], v0 offset:32768
	ds_read_b128 v[82:85], v0 offset:33792
	ds_read_b128 v[188:191], v0 offset:34816
	ds_read_b128 v[192:195], v0 offset:35840
	ds_read_b128 v[196:199], v0 offset:36864
	ds_read_b128 v[200:203], v0 offset:37888
	ds_read_b128 v[232:235], v0 offset:38912
	ds_read_b128 v[236:239], v0 offset:39936
	s_waitcnt vmcnt(2)
	s_barrier
	s_waitcnt lgkmcnt(0)
	s_setprio 1
	s_waitcnt lgkmcnt(7)
	v_mfma_f32_16x16x32_bf16 v[74:77], v[10:13], v[66:69], v[126:129]
	s_waitcnt lgkmcnt(6)
	v_mfma_f32_16x16x32_bf16 v[138:141], v[14:17], v[82:85], v[74:77]
	v_mfma_f32_16x16x32_bf16 v[74:77], v[180:183], v[66:69], v[122:125]
	v_mfma_f32_16x16x32_bf16 v[122:125], v[184:187], v[82:85], v[74:77]
	s_waitcnt lgkmcnt(5)
	v_mfma_f32_16x16x32_bf16 v[74:77], v[10:13], v[188:191], v[118:121]
	s_waitcnt lgkmcnt(4)
	v_mfma_f32_16x16x32_bf16 v[110:113], v[14:17], v[192:195], v[74:77]
	v_mfma_f32_16x16x32_bf16 v[74:77], v[180:183], v[188:191], v[114:117]
	v_mfma_f32_16x16x32_bf16 v[106:109], v[184:187], v[192:195], v[74:77]
	s_waitcnt lgkmcnt(3)
	v_mfma_f32_16x16x32_bf16 v[74:77], v[10:13], v[196:199], v[130:133]
	s_waitcnt lgkmcnt(2)
	v_mfma_f32_16x16x32_bf16 v[94:97], v[14:17], v[200:203], v[74:77]
	v_mfma_f32_16x16x32_bf16 v[74:77], v[180:183], v[196:199], v[160:163]
	v_mfma_f32_16x16x32_bf16 v[90:93], v[184:187], v[200:203], v[74:77]
	s_waitcnt lgkmcnt(1)
	v_mfma_f32_16x16x32_bf16 v[74:77], v[10:13], v[232:235], v[102:105]
	s_waitcnt lgkmcnt(0)
	v_mfma_f32_16x16x32_bf16 v[78:81], v[14:17], v[236:239], v[74:77]
	v_mfma_f32_16x16x32_bf16 v[74:77], v[180:183], v[232:235], v[98:101]
	v_mfma_f32_16x16x32_bf16 v[74:77], v[184:187], v[236:239], v[74:77]
	s_setprio 0
	s_barrier
	ds_read_b128 v[126:129], v151 offset:49152
	ds_read_b128 v[130:133], v151 offset:50176
	ds_read_b128 v[160:163], v151 offset:51200
	ds_read_b128 v[148:151], v151 offset:52224
	s_waitcnt vmcnt(0)
	s_barrier
	s_waitcnt lgkmcnt(0)
	s_setprio 1
	s_waitcnt lgkmcnt(3)
	v_mfma_f32_16x16x32_bf16 v[98:101], v[126:129], v[66:69], v[222:225]
	s_waitcnt lgkmcnt(1)
	v_mfma_f32_16x16x32_bf16 v[66:69], v[160:163], v[66:69], v[164:167]
	s_waitcnt lgkmcnt(0)
	v_mfma_f32_16x16x32_bf16 v[114:117], v[148:151], v[82:85], v[66:69]
	v_mfma_f32_16x16x32_bf16 v[66:69], v[126:129], v[188:191], v[86:89]
	v_mfma_f32_16x16x32_bf16 v[102:105], v[130:133], v[192:195], v[66:69]
	v_mfma_f32_16x16x32_bf16 v[66:69], v[160:163], v[188:191], v[70:73]
	v_mfma_f32_16x16x32_bf16 v[62:65], v[126:129], v[196:199], v[62:65]
	v_mfma_f32_16x16x32_bf16 v[58:61], v[160:163], v[196:199], v[58:61]
	v_mfma_f32_16x16x32_bf16 v[54:57], v[126:129], v[232:235], v[54:57]
	v_mfma_f32_16x16x32_bf16 v[50:53], v[160:163], v[232:235], v[50:53]
	v_mfma_f32_16x16x32_bf16 v[118:121], v[130:133], v[82:85], v[98:101]
	v_mfma_f32_16x16x32_bf16 v[98:101], v[148:151], v[192:195], v[66:69]
	v_mfma_f32_16x16x32_bf16 v[86:89], v[130:133], v[200:203], v[62:65]
	v_mfma_f32_16x16x32_bf16 v[82:85], v[148:151], v[200:203], v[58:61]
	v_mfma_f32_16x16x32_bf16 v[70:73], v[130:133], v[236:239], v[54:57]
	v_mfma_f32_16x16x32_bf16 v[66:69], v[148:151], v[236:239], v[50:53]
	s_setprio 0
	s_barrier
	s_nop 0
	ds_read_b128 v[50:53], v0 offset:49152
	ds_read_b128 v[164:167], v0 offset:50176
	ds_read_b128 v[188:191], v0 offset:51200
	ds_read_b128 v[192:195], v0 offset:52224
	ds_read_b128 v[196:199], v0 offset:53248
	ds_read_b128 v[200:203], v0 offset:54272
	ds_read_b128 v[222:225], v0 offset:55296
	ds_read_b128 v[232:235], v0 offset:56320
	s_barrier
	s_waitcnt lgkmcnt(0)
	s_setprio 1
	s_waitcnt lgkmcnt(7)
	v_mfma_f32_16x16x32_bf16 v[46:49], v[10:13], v[50:53], v[46:49]
	s_waitcnt lgkmcnt(5)
	v_mfma_f32_16x16x32_bf16 v[38:41], v[10:13], v[188:191], v[38:41]
	s_waitcnt lgkmcnt(3)
	v_mfma_f32_16x16x32_bf16 v[30:33], v[10:13], v[196:199], v[30:33]
	s_waitcnt lgkmcnt(1)
	v_mfma_f32_16x16x32_bf16 v[10:13], v[10:13], v[222:225], v[22:25]
	v_mfma_f32_16x16x32_bf16 v[62:65], v[14:17], v[164:167], v[46:49]
	v_mfma_f32_16x16x32_bf16 v[42:45], v[180:183], v[50:53], v[42:45]
	v_mfma_f32_16x16x32_bf16 v[46:49], v[14:17], v[192:195], v[38:41]
	v_mfma_f32_16x16x32_bf16 v[34:37], v[180:183], v[188:191], v[34:37]
	v_mfma_f32_16x16x32_bf16 v[30:33], v[14:17], v[200:203], v[30:33]
	v_mfma_f32_16x16x32_bf16 v[26:29], v[180:183], v[196:199], v[26:29]
	s_waitcnt lgkmcnt(0)
	v_mfma_f32_16x16x32_bf16 v[14:17], v[14:17], v[232:235], v[10:13]
	v_mfma_f32_16x16x32_bf16 v[10:13], v[180:183], v[222:225], v[18:21]
	v_mfma_f32_16x16x32_bf16 v[58:61], v[184:187], v[164:167], v[42:45]
	v_mfma_f32_16x16x32_bf16 v[42:45], v[184:187], v[192:195], v[34:37]
	v_mfma_f32_16x16x32_bf16 v[26:29], v[184:187], v[200:203], v[26:29]
	v_mfma_f32_16x16x32_bf16 v[10:13], v[184:187], v[232:235], v[10:13]
	s_setprio 0
	s_setprio 1
	v_mfma_f32_16x16x32_bf16 v[2:5], v[160:163], v[188:191], v[2:5]
	v_mfma_f32_16x16x32_bf16 v[18:21], v[126:129], v[50:53], v[134:137]
	v_mfma_f32_16x16x32_bf16 v[34:37], v[148:151], v[192:195], v[2:5]
	v_mfma_f32_16x16x32_bf16 v[2:5], v[126:129], v[196:199], v[156:159]
	v_mfma_f32_16x16x32_bf16 v[54:57], v[130:133], v[164:167], v[18:21]
	v_mfma_f32_16x16x32_bf16 v[18:21], v[160:163], v[50:53], v[152:155]
	v_mfma_f32_16x16x32_bf16 v[22:25], v[130:133], v[200:203], v[2:5]
	v_mfma_f32_16x16x32_bf16 v[2:5], v[160:163], v[196:199], v[168:171]
	v_mfma_f32_16x16x32_bf16 v[50:53], v[148:151], v[164:167], v[18:21]
	v_mfma_f32_16x16x32_bf16 v[6:9], v[126:129], v[188:191], v[6:9]
	v_mfma_f32_16x16x32_bf16 v[18:21], v[148:151], v[200:203], v[2:5]
	v_mfma_f32_16x16x32_bf16 v[2:5], v[126:129], v[222:225], v[172:175]
	v_mfma_f32_16x16x32_bf16 v[38:41], v[130:133], v[192:195], v[6:9]
	v_mfma_f32_16x16x32_bf16 v[6:9], v[130:133], v[232:235], v[2:5]
	v_mfma_f32_16x16x32_bf16 v[2:5], v[160:163], v[222:225], v[176:179]
	v_mfma_f32_16x16x32_bf16 v[2:5], v[148:151], v[232:235], v[2:5]
	s_setprio 0
	s_movk_i32 s0, 0x100
	v_cmp_gt_u32_e32 vcc, s0, v142
	s_barrier
	s_and_saveexec_b64 s[0:1], vcc
	s_cbranch_execz .LBB0_37
	s_barrier

.LBB0_85:
	ds_read_b128 v[164:167], v151
	ds_read_b128 v[168:171], v151 offset:1024
	ds_read_b128 v[172:175], v151 offset:2048
	ds_read_b128 v[176:179], v151 offset:3072
	v_lshl_add_u64 v[204:205], v[138:139], 0, s[10:11]
	v_lshl_add_u64 v[228:229], v[204:205], 0, s[60:61]
	s_add_i32 m0, s1, 0xc000
	ds_read_b128 v[180:183], v0
	ds_read_b128 v[184:187], v0 offset:1024
	ds_read_b128 v[188:191], v0 offset:2048
	ds_read_b128 v[192:195], v0 offset:3072
	ds_read_b128 v[196:199], v0 offset:4096
	ds_read_b128 v[200:203], v0 offset:5120
	ds_read_b128 v[222:225], v0 offset:6144
	ds_read_b128 v[232:235], v0 offset:7168
	global_load_lds_dwordx4 v[228:229], off
	v_lshl_add_u64 v[210:211], v[140:141], 0, s[10:11]
	s_add_i32 m0, s1, 0xe000
	v_lshl_add_u64 v[152:153], v[210:211], 0, s[60:61]
	global_load_lds_dwordx4 v[152:153], off
	s_barrier
	s_waitcnt lgkmcnt(0)
	v_mfma_f32_16x16x32_bf16 v[126:129], v[164:167], v[180:183], v[126:129]
	v_mfma_f32_16x16x32_bf16 v[122:125], v[172:175], v[180:183], v[122:125]
	v_mfma_f32_16x16x32_bf16 v[118:121], v[164:167], v[188:191], v[118:121]
	v_mfma_f32_16x16x32_bf16 v[114:117], v[172:175], v[188:191], v[114:117]
	v_mfma_f32_16x16x32_bf16 v[110:113], v[164:167], v[196:199], v[110:113]
	v_mfma_f32_16x16x32_bf16 v[106:109], v[172:175], v[196:199], v[106:109]
	v_mfma_f32_16x16x32_bf16 v[102:105], v[164:167], v[222:225], v[102:105]
	v_mfma_f32_16x16x32_bf16 v[98:101], v[172:175], v[222:225], v[98:101]
	v_mfma_f32_16x16x32_bf16 v[126:129], v[168:171], v[184:187], v[126:129]
	v_mfma_f32_16x16x32_bf16 v[122:125], v[176:179], v[184:187], v[122:125]
	v_mfma_f32_16x16x32_bf16 v[118:121], v[168:171], v[192:195], v[118:121]
	v_mfma_f32_16x16x32_bf16 v[114:117], v[176:179], v[192:195], v[114:117]
	v_mfma_f32_16x16x32_bf16 v[110:113], v[168:171], v[200:203], v[110:113]
	v_mfma_f32_16x16x32_bf16 v[106:109], v[176:179], v[200:203], v[106:109]
	v_mfma_f32_16x16x32_bf16 v[102:105], v[168:171], v[232:235], v[102:105]
	v_mfma_f32_16x16x32_bf16 v[98:101], v[176:179], v[232:235], v[98:101]
	s_barrier
	v_lshl_add_u64 v[216:217], v[134:135], 0, s[10:11]
	s_add_i32 m0, s1, 0xff00
	ds_read_b128 v[236:239], v151 offset:16384
	ds_read_b128 v[240:243], v151 offset:17408
	ds_read_b128 v[244:247], v151 offset:18432
	ds_read_b128 v[248:251], v151 offset:19456
	global_load_lds_dwordx4 v[216:217], off offset:256
	s_add_i32 m0, s1, 0x11f00
	v_lshl_add_u64 v[218:219], v[136:137], 0, s[10:11]
	global_load_lds_dwordx4 v[218:219], off offset:256
	s_barrier
	s_waitcnt lgkmcnt(0)
	v_mfma_f32_16x16x32_bf16 v[94:97], v[236:239], v[180:183], v[94:97]
	v_mfma_f32_16x16x32_bf16 v[90:93], v[244:247], v[180:183], v[90:93]
	v_mfma_f32_16x16x32_bf16 v[86:89], v[236:239], v[188:191], v[86:89]
	v_mfma_f32_16x16x32_bf16 v[82:85], v[244:247], v[188:191], v[82:85]
	v_mfma_f32_16x16x32_bf16 v[78:81], v[236:239], v[196:199], v[78:81]
	v_mfma_f32_16x16x32_bf16 v[74:77], v[244:247], v[196:199], v[74:77]
	v_mfma_f32_16x16x32_bf16 v[70:73], v[236:239], v[222:225], v[70:73]
	v_mfma_f32_16x16x32_bf16 v[66:69], v[244:247], v[222:225], v[66:69]
	v_mfma_f32_16x16x32_bf16 v[94:97], v[240:243], v[184:187], v[94:97]
	v_mfma_f32_16x16x32_bf16 v[90:93], v[248:251], v[184:187], v[90:93]
	v_mfma_f32_16x16x32_bf16 v[86:89], v[240:243], v[192:195], v[86:89]
	v_mfma_f32_16x16x32_bf16 v[82:85], v[248:251], v[192:195], v[82:85]
	v_mfma_f32_16x16x32_bf16 v[78:81], v[240:243], v[200:203], v[78:81]
	v_mfma_f32_16x16x32_bf16 v[74:77], v[248:251], v[200:203], v[74:77]
	v_mfma_f32_16x16x32_bf16 v[70:73], v[240:243], v[232:235], v[70:73]
	v_mfma_f32_16x16x32_bf16 v[66:69], v[248:251], v[232:235], v[66:69]
	v_lshl_add_u64 v[158:159], v[204:205], 0, s[74:75]
	s_mov_b32 m0, s1
	s_barrier
	ds_read_b128 v[180:183], v0 offset:16384
	ds_read_b128 v[184:187], v0 offset:17408
	ds_read_b128 v[188:191], v0 offset:18432
	ds_read_b128 v[192:195], v0 offset:19456
	ds_read_b128 v[196:199], v0 offset:20480
	ds_read_b128 v[200:203], v0 offset:21504
	ds_read_b128 v[222:225], v0 offset:22528
	ds_read_b128 v[232:235], v0 offset:23552
	global_load_lds_dwordx4 v[158:159], off
	s_add_i32 m0, s1, 0x1f00
	s_nop 0
	global_load_lds_dwordx4 v[210:211], off offset:256
	s_barrier
	s_waitcnt lgkmcnt(0)
	v_mfma_f32_16x16x32_bf16 v[62:65], v[164:167], v[180:183], v[62:65]
	v_mfma_f32_16x16x32_bf16 v[58:61], v[172:175], v[180:183], v[58:61]
	v_mfma_f32_16x16x32_bf16 v[54:57], v[164:167], v[188:191], v[54:57]
	v_mfma_f32_16x16x32_bf16 v[50:53], v[172:175], v[188:191], v[50:53]
	v_mfma_f32_16x16x32_bf16 v[46:49], v[164:167], v[196:199], v[46:49]
	v_mfma_f32_16x16x32_bf16 v[42:45], v[172:175], v[196:199], v[42:45]
	v_mfma_f32_16x16x32_bf16 v[38:41], v[164:167], v[222:225], v[38:41]
	v_mfma_f32_16x16x32_bf16 v[34:37], v[172:175], v[222:225], v[34:37]
	v_mfma_f32_16x16x32_bf16 v[62:65], v[168:171], v[184:187], v[62:65]
	v_mfma_f32_16x16x32_bf16 v[58:61], v[176:179], v[184:187], v[58:61]
	v_mfma_f32_16x16x32_bf16 v[54:57], v[168:171], v[192:195], v[54:57]
	v_mfma_f32_16x16x32_bf16 v[50:53], v[176:179], v[192:195], v[50:53]
	v_mfma_f32_16x16x32_bf16 v[46:49], v[168:171], v[200:203], v[46:49]
	v_mfma_f32_16x16x32_bf16 v[42:45], v[176:179], v[200:203], v[42:45]
	v_mfma_f32_16x16x32_bf16 v[38:41], v[168:171], v[232:235], v[38:41]
	v_mfma_f32_16x16x32_bf16 v[34:37], v[176:179], v[232:235], v[34:37]
	s_barrier
	s_add_i32 m0, s1, 0x14000
	v_lshl_add_u64 v[154:155], v[216:217], 0, s[18:19]
	global_load_lds_dwordx4 v[154:155], off
	s_add_i32 m0, s1, 0x16000
	v_lshl_add_u64 v[156:157], v[218:219], 0, s[18:19]
	global_load_lds_dwordx4 v[156:157], off
	s_waitcnt vmcnt(6)
	s_barrier
	v_mfma_f32_16x16x32_bf16 v[30:33], v[236:239], v[180:183], v[30:33]
	v_mfma_f32_16x16x32_bf16 v[26:29], v[244:247], v[180:183], v[26:29]
	v_mfma_f32_16x16x32_bf16 v[22:25], v[236:239], v[188:191], v[22:25]
	v_mfma_f32_16x16x32_bf16 v[18:21], v[244:247], v[188:191], v[18:21]
	v_mfma_f32_16x16x32_bf16 v[14:17], v[236:239], v[196:199], v[14:17]
	v_mfma_f32_16x16x32_bf16 v[10:13], v[244:247], v[196:199], v[10:13]
	v_mfma_f32_16x16x32_bf16 v[6:9], v[236:239], v[222:225], v[6:9]
	v_mfma_f32_16x16x32_bf16 v[2:5], v[244:247], v[222:225], v[2:5]
	v_mfma_f32_16x16x32_bf16 v[30:33], v[240:243], v[184:187], v[30:33]
	v_mfma_f32_16x16x32_bf16 v[26:29], v[248:251], v[184:187], v[26:29]
	v_mfma_f32_16x16x32_bf16 v[22:25], v[240:243], v[192:195], v[22:25]
	v_mfma_f32_16x16x32_bf16 v[18:21], v[248:251], v[192:195], v[18:21]
	v_mfma_f32_16x16x32_bf16 v[14:17], v[240:243], v[200:203], v[14:17]
	v_mfma_f32_16x16x32_bf16 v[10:13], v[248:251], v[200:203], v[10:13]
	v_mfma_f32_16x16x32_bf16 v[6:9], v[240:243], v[232:235], v[6:9]
	v_mfma_f32_16x16x32_bf16 v[2:5], v[248:251], v[232:235], v[2:5]
	s_barrier
	ds_read_b128 v[164:167], v151 offset:32768
	ds_read_b128 v[168:171], v151 offset:33792
	ds_read_b128 v[172:175], v151 offset:34816
	ds_read_b128 v[176:179], v151 offset:35840
	s_add_i32 m0, s1, 0x3f80
	ds_read_b128 v[180:183], v0 offset:32768
	ds_read_b128 v[184:187], v0 offset:33792
	ds_read_b128 v[188:191], v0 offset:34816
	ds_read_b128 v[192:195], v0 offset:35840
	ds_read_b128 v[196:199], v0 offset:36864
	ds_read_b128 v[200:203], v0 offset:37888
	ds_read_b128 v[222:225], v0 offset:38912
	ds_read_b128 v[232:235], v0 offset:39936
	global_load_lds_dwordx4 v[228:229], off offset:128
	s_add_i32 m0, s1, 0x5f80
	s_nop 0
	global_load_lds_dwordx4 v[152:153], off offset:128
	s_barrier
	s_waitcnt lgkmcnt(0)
	v_mfma_f32_16x16x32_bf16 v[126:129], v[164:167], v[180:183], v[126:129]
	v_mfma_f32_16x16x32_bf16 v[122:125], v[172:175], v[180:183], v[122:125]
	v_mfma_f32_16x16x32_bf16 v[118:121], v[164:167], v[188:191], v[118:121]
	v_mfma_f32_16x16x32_bf16 v[114:117], v[172:175], v[188:191], v[114:117]
	v_mfma_f32_16x16x32_bf16 v[110:113], v[164:167], v[196:199], v[110:113]
	v_mfma_f32_16x16x32_bf16 v[106:109], v[172:175], v[196:199], v[106:109]
	v_mfma_f32_16x16x32_bf16 v[102:105], v[164:167], v[222:225], v[102:105]
	v_mfma_f32_16x16x32_bf16 v[98:101], v[172:175], v[222:225], v[98:101]
	v_mfma_f32_16x16x32_bf16 v[126:129], v[168:171], v[184:187], v[126:129]
	v_mfma_f32_16x16x32_bf16 v[122:125], v[176:179], v[184:187], v[122:125]
	v_mfma_f32_16x16x32_bf16 v[118:121], v[168:171], v[192:195], v[118:121]
	v_mfma_f32_16x16x32_bf16 v[114:117], v[176:179], v[192:195], v[114:117]
	v_mfma_f32_16x16x32_bf16 v[110:113], v[168:171], v[200:203], v[110:113]
	v_mfma_f32_16x16x32_bf16 v[106:109], v[176:179], v[200:203], v[106:109]
	v_mfma_f32_16x16x32_bf16 v[102:105], v[168:171], v[232:235], v[102:105]
	v_mfma_f32_16x16x32_bf16 v[98:101], v[176:179], v[232:235], v[98:101]
	s_barrier
	s_add_i32 m0, s1, 0x17e80
	ds_read_b128 v[236:239], v151 offset:49152
	ds_read_b128 v[240:243], v151 offset:50176
	ds_read_b128 v[244:247], v151 offset:51200
	ds_read_b128 v[248:251], v151 offset:52224
	global_load_lds_dwordx4 v[216:217], off offset:384
	s_add_i32 m0, s1, 0x19e80
	s_nop 0
	global_load_lds_dwordx4 v[218:219], off offset:384
	s_barrier
	s_waitcnt lgkmcnt(0)
	v_mfma_f32_16x16x32_bf16 v[94:97], v[236:239], v[180:183], v[94:97]
	v_mfma_f32_16x16x32_bf16 v[90:93], v[244:247], v[180:183], v[90:93]
	v_mfma_f32_16x16x32_bf16 v[86:89], v[236:239], v[188:191], v[86:89]
	v_mfma_f32_16x16x32_bf16 v[82:85], v[244:247], v[188:191], v[82:85]
	v_mfma_f32_16x16x32_bf16 v[78:81], v[236:239], v[196:199], v[78:81]
	v_mfma_f32_16x16x32_bf16 v[74:77], v[244:247], v[196:199], v[74:77]
	v_mfma_f32_16x16x32_bf16 v[70:73], v[236:239], v[222:225], v[70:73]
	v_mfma_f32_16x16x32_bf16 v[66:69], v[244:247], v[222:225], v[66:69]
	v_mfma_f32_16x16x32_bf16 v[94:97], v[240:243], v[184:187], v[94:97]
	v_mfma_f32_16x16x32_bf16 v[90:93], v[248:251], v[184:187], v[90:93]
	v_mfma_f32_16x16x32_bf16 v[86:89], v[240:243], v[192:195], v[86:89]
	v_mfma_f32_16x16x32_bf16 v[82:85], v[248:251], v[192:195], v[82:85]
	v_mfma_f32_16x16x32_bf16 v[78:81], v[240:243], v[200:203], v[78:81]
	v_mfma_f32_16x16x32_bf16 v[74:77], v[248:251], v[200:203], v[74:77]
	v_mfma_f32_16x16x32_bf16 v[70:73], v[240:243], v[232:235], v[70:73]
	v_mfma_f32_16x16x32_bf16 v[66:69], v[248:251], v[232:235], v[66:69]
	s_add_i32 m0, s1, 0x7e80
	s_barrier
	ds_read_b128 v[180:183], v0 offset:49152
	ds_read_b128 v[184:187], v0 offset:50176
	ds_read_b128 v[188:191], v0 offset:51200
	ds_read_b128 v[192:195], v0 offset:52224
	ds_read_b128 v[196:199], v0 offset:53248
	ds_read_b128 v[200:203], v0 offset:54272
	ds_read_b128 v[222:225], v0 offset:55296
	ds_read_b128 v[232:235], v0 offset:56320
	global_load_lds_dwordx4 v[204:205], off offset:384
	s_add_i32 m0, s1, 0x9e80
	s_nop 0
	global_load_lds_dwordx4 v[210:211], off offset:384
	s_barrier
	s_waitcnt lgkmcnt(0)
	v_mfma_f32_16x16x32_bf16 v[62:65], v[164:167], v[180:183], v[62:65]
	v_mfma_f32_16x16x32_bf16 v[58:61], v[172:175], v[180:183], v[58:61]
	v_mfma_f32_16x16x32_bf16 v[54:57], v[164:167], v[188:191], v[54:57]
	v_mfma_f32_16x16x32_bf16 v[50:53], v[172:175], v[188:191], v[50:53]
	v_mfma_f32_16x16x32_bf16 v[46:49], v[164:167], v[196:199], v[46:49]
	v_mfma_f32_16x16x32_bf16 v[42:45], v[172:175], v[196:199], v[42:45]
	v_mfma_f32_16x16x32_bf16 v[38:41], v[164:167], v[222:225], v[38:41]
	v_mfma_f32_16x16x32_bf16 v[34:37], v[172:175], v[222:225], v[34:37]
	v_mfma_f32_16x16x32_bf16 v[62:65], v[168:171], v[184:187], v[62:65]
	v_mfma_f32_16x16x32_bf16 v[58:61], v[176:179], v[184:187], v[58:61]
	v_mfma_f32_16x16x32_bf16 v[54:57], v[168:171], v[192:195], v[54:57]
	v_mfma_f32_16x16x32_bf16 v[50:53], v[176:179], v[192:195], v[50:53]
	v_mfma_f32_16x16x32_bf16 v[46:49], v[168:171], v[200:203], v[46:49]
	v_mfma_f32_16x16x32_bf16 v[42:45], v[176:179], v[200:203], v[42:45]
	v_mfma_f32_16x16x32_bf16 v[38:41], v[168:171], v[232:235], v[38:41]
	v_mfma_f32_16x16x32_bf16 v[34:37], v[176:179], v[232:235], v[34:37]
	s_barrier
	s_add_i32 m0, s1, 0x1bf80
	s_nop 0
	global_load_lds_dwordx4 v[154:155], off offset:128
	s_add_i32 m0, s1, 0x1df80
	s_nop 0
	global_load_lds_dwordx4 v[156:157], off offset:128
	s_waitcnt vmcnt(6)
	s_barrier
	v_mfma_f32_16x16x32_bf16 v[30:33], v[236:239], v[180:183], v[30:33]
	v_mfma_f32_16x16x32_bf16 v[26:29], v[244:247], v[180:183], v[26:29]
	v_mfma_f32_16x16x32_bf16 v[22:25], v[236:239], v[188:191], v[22:25]
	v_mfma_f32_16x16x32_bf16 v[18:21], v[244:247], v[188:191], v[18:21]
	v_mfma_f32_16x16x32_bf16 v[14:17], v[236:239], v[196:199], v[14:17]
	v_mfma_f32_16x16x32_bf16 v[10:13], v[244:247], v[196:199], v[10:13]
	v_mfma_f32_16x16x32_bf16 v[6:9], v[236:239], v[222:225], v[6:9]
	v_mfma_f32_16x16x32_bf16 v[2:5], v[244:247], v[222:225], v[2:5]
	v_mfma_f32_16x16x32_bf16 v[30:33], v[240:243], v[184:187], v[30:33]
	v_mfma_f32_16x16x32_bf16 v[26:29], v[248:251], v[184:187], v[26:29]
	v_mfma_f32_16x16x32_bf16 v[22:25], v[240:243], v[192:195], v[22:25]
	v_mfma_f32_16x16x32_bf16 v[18:21], v[248:251], v[192:195], v[18:21]
	v_mfma_f32_16x16x32_bf16 v[14:17], v[240:243], v[200:203], v[14:17]
	v_mfma_f32_16x16x32_bf16 v[10:13], v[248:251], v[200:203], v[10:13]
	v_mfma_f32_16x16x32_bf16 v[6:9], v[240:243], v[232:235], v[6:9]
	v_mfma_f32_16x16x32_bf16 v[2:5], v[248:251], v[232:235], v[2:5]
	s_add_i32 s0, s0, 2
	s_add_u32 s10, s10, 0x100
	s_addc_u32 s11, s11, 0
	s_cmp_lt_u32 s0, 28
	s_barrier
	s_cbranch_scc1 .LBB0_85
	s_add_i32 s1, s1, 0x1e000
	s_mov_b64 s[10:11], 0xf80
	v_readfirstlane_b32 s0, v162
	v_lshl_add_u64 v[132:133], v[132:133], 0, s[10:11]
	s_mov_b32 m0, s0
	v_readfirstlane_b32 s0, v163
	ds_read_b128 v[134:137], v151
	ds_read_b128 v[138:141], v151 offset:1024
	ds_read_b128 v[152:155], v151 offset:2048
	ds_read_b128 v[156:159], v151 offset:3072
	ds_read_b128 v[164:167], v0
	ds_read_b128 v[168:171], v0 offset:1024
	ds_read_b128 v[172:175], v0 offset:2048
	ds_read_b128 v[176:179], v0 offset:3072
	ds_read_b128 v[180:183], v0 offset:4096
	ds_read_b128 v[184:187], v0 offset:5120
	ds_read_b128 v[188:191], v0 offset:6144
	ds_read_b128 v[192:195], v0 offset:7168
	global_load_lds_dwordx4 v[132:133], off
	v_lshl_add_u64 v[130:131], v[130:131], 0, s[10:11]
	s_mov_b32 m0, s0
	s_nop 0
	global_load_lds_dwordx4 v[130:131], off
	s_barrier
	s_waitcnt lgkmcnt(0)
	s_setprio 1
	s_waitcnt lgkmcnt(0)
	v_mfma_f32_16x16x32_bf16 v[126:129], v[134:137], v[164:167], v[126:129]
	v_mfma_f32_16x16x32_bf16 v[122:125], v[152:155], v[164:167], v[122:125]
	v_mfma_f32_16x16x32_bf16 v[114:117], v[152:155], v[172:175], v[114:117]
	v_mfma_f32_16x16x32_bf16 v[106:109], v[152:155], v[180:183], v[106:109]
	v_mfma_f32_16x16x32_bf16 v[98:101], v[152:155], v[188:191], v[98:101]
	v_mfma_f32_16x16x32_bf16 v[126:129], v[138:141], v[168:171], v[126:129]
	v_mfma_f32_16x16x32_bf16 v[122:125], v[156:159], v[168:171], v[122:125]
	v_mfma_f32_16x16x32_bf16 v[118:121], v[134:137], v[172:175], v[118:121]
	v_mfma_f32_16x16x32_bf16 v[114:117], v[156:159], v[176:179], v[114:117]
	v_mfma_f32_16x16x32_bf16 v[110:113], v[134:137], v[180:183], v[110:113]
	v_mfma_f32_16x16x32_bf16 v[106:109], v[156:159], v[184:187], v[106:109]
	v_mfma_f32_16x16x32_bf16 v[102:105], v[134:137], v[188:191], v[102:105]
	v_mfma_f32_16x16x32_bf16 v[98:101], v[156:159], v[192:195], v[98:101]
	v_mfma_f32_16x16x32_bf16 v[130:133], v[138:141], v[176:179], v[118:121]
	v_mfma_f32_16x16x32_bf16 v[160:163], v[138:141], v[184:187], v[110:113]
	v_mfma_f32_16x16x32_bf16 v[196:199], v[138:141], v[192:195], v[102:105]
	s_setprio 0
	s_barrier
	s_nop 0
	ds_read_b128 v[102:105], v151 offset:16384
	ds_read_b128 v[110:113], v151 offset:17408
	ds_read_b128 v[118:121], v151 offset:18432
	ds_read_b128 v[200:203], v151 offset:19456
	s_barrier
	s_waitcnt lgkmcnt(0)
	s_setprio 1
	s_waitcnt lgkmcnt(1)
	v_mfma_f32_16x16x32_bf16 v[90:93], v[118:121], v[164:167], v[90:93]
	v_mfma_f32_16x16x32_bf16 v[86:89], v[102:105], v[172:175], v[86:89]
	v_mfma_f32_16x16x32_bf16 v[82:85], v[118:121], v[172:175], v[82:85]
	v_mfma_f32_16x16x32_bf16 v[78:81], v[102:105], v[180:183], v[78:81]
	v_mfma_f32_16x16x32_bf16 v[70:73], v[102:105], v[188:191], v[70:73]
	v_mfma_f32_16x16x32_bf16 v[94:97], v[102:105], v[164:167], v[94:97]
	s_waitcnt lgkmcnt(0)
	v_mfma_f32_16x16x32_bf16 v[90:93], v[200:203], v[168:171], v[90:93]
	v_mfma_f32_16x16x32_bf16 v[86:89], v[110:113], v[176:179], v[86:89]
	v_mfma_f32_16x16x32_bf16 v[82:85], v[200:203], v[176:179], v[82:85]
	v_mfma_f32_16x16x32_bf16 v[78:81], v[110:113], v[184:187], v[78:81]
	v_mfma_f32_16x16x32_bf16 v[74:77], v[118:121], v[180:183], v[74:77]
	v_mfma_f32_16x16x32_bf16 v[70:73], v[110:113], v[192:195], v[70:73]
	v_mfma_f32_16x16x32_bf16 v[66:69], v[118:121], v[188:191], v[66:69]
	v_mfma_f32_16x16x32_bf16 v[222:225], v[110:113], v[168:171], v[94:97]
	v_mfma_f32_16x16x32_bf16 v[164:167], v[200:203], v[184:187], v[74:77]
	v_mfma_f32_16x16x32_bf16 v[168:171], v[200:203], v[192:195], v[66:69]
	s_setprio 0
	s_barrier
	s_nop 2
	ds_read_b128 v[66:69], v0 offset:16384
	ds_read_b128 v[74:77], v0 offset:17408
	ds_read_b128 v[94:97], v0 offset:18432
	ds_read_b128 v[172:175], v0 offset:19456
	ds_read_b128 v[176:179], v0 offset:20480
	ds_read_b128 v[180:183], v0 offset:21504
	ds_read_b128 v[184:187], v0 offset:22528
	ds_read_b128 v[188:191], v0 offset:23552
	s_waitcnt vmcnt(4)
	s_barrier
	s_waitcnt lgkmcnt(0)
	s_setprio 1
	s_waitcnt lgkmcnt(5)
	v_mfma_f32_16x16x32_bf16 v[54:57], v[134:137], v[94:97], v[54:57]
	v_mfma_f32_16x16x32_bf16 v[50:53], v[152:155], v[94:97], v[50:53]
	v_mfma_f32_16x16x32_bf16 v[62:65], v[134:137], v[66:69], v[62:65]
	v_mfma_f32_16x16x32_bf16 v[58:61], v[152:155], v[66:69], v[58:61]
	s_waitcnt lgkmcnt(4)
	v_mfma_f32_16x16x32_bf16 v[54:57], v[138:141], v[172:175], v[54:57]
	v_mfma_f32_16x16x32_bf16 v[50:53], v[156:159], v[172:175], v[50:53]
	s_waitcnt lgkmcnt(3)
	v_mfma_f32_16x16x32_bf16 v[46:49], v[134:137], v[176:179], v[46:49]
	v_mfma_f32_16x16x32_bf16 v[42:45], v[152:155], v[176:179], v[42:45]
	s_waitcnt lgkmcnt(1)
	v_mfma_f32_16x16x32_bf16 v[38:41], v[134:137], v[184:187], v[38:41]
	v_mfma_f32_16x16x32_bf16 v[34:37], v[152:155], v[184:187], v[34:37]
	v_mfma_f32_16x16x32_bf16 v[192:195], v[138:141], v[74:77], v[62:65]
	v_mfma_f32_16x16x32_bf16 v[232:235], v[156:159], v[74:77], v[58:61]
	v_mfma_f32_16x16x32_bf16 v[236:239], v[138:141], v[180:183], v[46:49]
	v_mfma_f32_16x16x32_bf16 v[240:243], v[156:159], v[180:183], v[42:45]
	s_waitcnt lgkmcnt(0)
	v_mfma_f32_16x16x32_bf16 v[134:137], v[138:141], v[188:191], v[38:41]
	v_mfma_f32_16x16x32_bf16 v[138:141], v[156:159], v[188:191], v[34:37]
	s_setprio 0
	s_setprio 1
	v_mfma_f32_16x16x32_bf16 v[30:33], v[102:105], v[66:69], v[30:33]
	v_mfma_f32_16x16x32_bf16 v[26:29], v[118:121], v[66:69], v[26:29]
	v_mfma_f32_16x16x32_bf16 v[14:17], v[102:105], v[176:179], v[14:17]
	v_mfma_f32_16x16x32_bf16 v[10:13], v[118:121], v[176:179], v[10:13]
	v_mfma_f32_16x16x32_bf16 v[30:33], v[110:113], v[74:77], v[30:33]
	v_mfma_f32_16x16x32_bf16 v[26:29], v[200:203], v[74:77], v[26:29]
	v_mfma_f32_16x16x32_bf16 v[22:25], v[102:105], v[94:97], v[22:25]
	v_mfma_f32_16x16x32_bf16 v[18:21], v[118:121], v[94:97], v[18:21]
	v_mfma_f32_16x16x32_bf16 v[14:17], v[110:113], v[180:183], v[14:17]
	v_mfma_f32_16x16x32_bf16 v[10:13], v[200:203], v[180:183], v[10:13]
	v_mfma_f32_16x16x32_bf16 v[6:9], v[102:105], v[184:187], v[6:9]
	v_mfma_f32_16x16x32_bf16 v[2:5], v[118:121], v[184:187], v[2:5]
	v_mfma_f32_16x16x32_bf16 v[152:155], v[110:113], v[172:175], v[22:25]
	v_mfma_f32_16x16x32_bf16 v[156:159], v[200:203], v[172:175], v[18:21]
	v_mfma_f32_16x16x32_bf16 v[172:175], v[110:113], v[188:191], v[6:9]
	v_mfma_f32_16x16x32_bf16 v[176:179], v[200:203], v[188:191], v[2:5]
	s_setprio 0
	s_barrier
	s_nop 1
	ds_read_b128 v[2:5], v151 offset:32768
	ds_read_b128 v[6:9], v151 offset:33792
	ds_read_b128 v[180:183], v151 offset:34816
	ds_read_b128 v[184:187], v151 offset:35840
	ds_read_b128 v[18:21], v0 offset:32768
	ds_read_b128 v[22:25], v0 offset:33792
	ds_read_b128 v[38:41], v0 offset:34816
	ds_read_b128 v[46:49], v0 offset:35840
	ds_read_b128 v[58:61], v0 offset:36864
	ds_read_b128 v[66:69], v0 offset:37888
	ds_read_b128 v[188:191], v0 offset:38912
	ds_read_b128 v[200:203], v0 offset:39936
	s_waitcnt vmcnt(2)
	s_barrier
	s_waitcnt lgkmcnt(0)
	s_setprio 1
	s_waitcnt lgkmcnt(7)
	v_mfma_f32_16x16x32_bf16 v[34:37], v[2:5], v[18:21], v[126:129]
	s_waitcnt lgkmcnt(6)
	v_mfma_f32_16x16x32_bf16 v[118:121], v[6:9], v[22:25], v[34:37]
	v_mfma_f32_16x16x32_bf16 v[34:37], v[180:183], v[18:21], v[122:125]
	v_mfma_f32_16x16x32_bf16 v[110:113], v[184:187], v[22:25], v[34:37]
	s_waitcnt lgkmcnt(5)
	v_mfma_f32_16x16x32_bf16 v[34:37], v[2:5], v[38:41], v[130:133]
	s_waitcnt lgkmcnt(4)
	v_mfma_f32_16x16x32_bf16 v[102:105], v[6:9], v[46:49], v[34:37]
	v_mfma_f32_16x16x32_bf16 v[34:37], v[180:183], v[38:41], v[114:117]
	v_mfma_f32_16x16x32_bf16 v[94:97], v[184:187], v[46:49], v[34:37]
	s_waitcnt lgkmcnt(3)
	v_mfma_f32_16x16x32_bf16 v[34:37], v[2:5], v[58:61], v[160:163]
	s_waitcnt lgkmcnt(2)
	v_mfma_f32_16x16x32_bf16 v[74:77], v[6:9], v[66:69], v[34:37]
	v_mfma_f32_16x16x32_bf16 v[34:37], v[180:183], v[58:61], v[106:109]
	v_mfma_f32_16x16x32_bf16 v[62:65], v[184:187], v[66:69], v[34:37]
	s_waitcnt lgkmcnt(1)
	v_mfma_f32_16x16x32_bf16 v[34:37], v[2:5], v[188:191], v[196:199]
	s_waitcnt lgkmcnt(0)
	v_mfma_f32_16x16x32_bf16 v[42:45], v[6:9], v[200:203], v[34:37]
	v_mfma_f32_16x16x32_bf16 v[34:37], v[180:183], v[188:191], v[98:101]
	v_mfma_f32_16x16x32_bf16 v[34:37], v[184:187], v[200:203], v[34:37]
	s_setprio 0
	s_barrier
	ds_read_b128 v[130:133], v151 offset:49152
	ds_read_b128 v[160:163], v151 offset:50176
	ds_read_b128 v[196:199], v151 offset:51200
	ds_read_b128 v[148:151], v151 offset:52224
	s_waitcnt vmcnt(0)
	s_barrier
	s_waitcnt lgkmcnt(0)
	s_setprio 1
	s_waitcnt lgkmcnt(3)
	v_mfma_f32_16x16x32_bf16 v[98:101], v[130:133], v[18:21], v[222:225]
	s_waitcnt lgkmcnt(1)
	v_mfma_f32_16x16x32_bf16 v[18:21], v[196:199], v[18:21], v[90:93]
	s_waitcnt lgkmcnt(0)
	v_mfma_f32_16x16x32_bf16 v[122:125], v[148:151], v[22:25], v[18:21]
	v_mfma_f32_16x16x32_bf16 v[18:21], v[130:133], v[38:41], v[86:89]
	v_mfma_f32_16x16x32_bf16 v[114:117], v[160:163], v[46:49], v[18:21]
	v_mfma_f32_16x16x32_bf16 v[18:21], v[196:199], v[38:41], v[82:85]
	v_mfma_f32_16x16x32_bf16 v[106:109], v[148:151], v[46:49], v[18:21]
	v_mfma_f32_16x16x32_bf16 v[18:21], v[130:133], v[58:61], v[78:81]
	v_mfma_f32_16x16x32_bf16 v[126:129], v[160:163], v[22:25], v[98:101]
	v_mfma_f32_16x16x32_bf16 v[98:101], v[160:163], v[66:69], v[18:21]
	v_mfma_f32_16x16x32_bf16 v[18:21], v[196:199], v[58:61], v[164:167]
	v_mfma_f32_16x16x32_bf16 v[90:93], v[148:151], v[66:69], v[18:21]
	v_mfma_f32_16x16x32_bf16 v[18:21], v[130:133], v[188:191], v[70:73]
	v_mfma_f32_16x16x32_bf16 v[66:69], v[160:163], v[200:203], v[18:21]
	v_mfma_f32_16x16x32_bf16 v[18:21], v[196:199], v[188:191], v[168:171]
	v_mfma_f32_16x16x32_bf16 v[58:61], v[148:151], v[200:203], v[18:21]
	s_setprio 0
	s_barrier
	ds_read_b128 v[82:85], v0 offset:49152
	ds_read_b128 v[164:167], v0 offset:50176
	ds_read_b128 v[168:171], v0 offset:51200
	ds_read_b128 v[188:191], v0 offset:52224
	ds_read_b128 v[200:203], v0 offset:53248
	ds_read_b128 v[222:225], v0 offset:54272
	ds_read_b128 v[244:247], v0 offset:55296
	ds_read_b128 v[248:251], v0 offset:56320
	s_barrier
	s_waitcnt lgkmcnt(0)
	s_setprio 1
	s_waitcnt lgkmcnt(7)
	v_mfma_f32_16x16x32_bf16 v[18:21], v[2:5], v[82:85], v[192:195]
	s_waitcnt lgkmcnt(6)
	v_mfma_f32_16x16x32_bf16 v[78:81], v[6:9], v[164:167], v[18:21]
	v_mfma_f32_16x16x32_bf16 v[18:21], v[180:183], v[82:85], v[232:235]
	v_mfma_f32_16x16x32_bf16 v[70:73], v[184:187], v[164:167], v[18:21]
	s_waitcnt lgkmcnt(5)
	v_mfma_f32_16x16x32_bf16 v[18:21], v[2:5], v[168:171], v[54:57]
	s_waitcnt lgkmcnt(4)
	v_mfma_f32_16x16x32_bf16 v[46:49], v[6:9], v[188:191], v[18:21]
	v_mfma_f32_16x16x32_bf16 v[18:21], v[180:183], v[168:171], v[50:53]
	v_mfma_f32_16x16x32_bf16 v[38:41], v[184:187], v[188:191], v[18:21]
	s_waitcnt lgkmcnt(3)
	v_mfma_f32_16x16x32_bf16 v[18:21], v[2:5], v[200:203], v[236:239]
	s_waitcnt lgkmcnt(1)
	v_mfma_f32_16x16x32_bf16 v[2:5], v[2:5], v[244:247], v[134:137]
	v_mfma_f32_16x16x32_bf16 v[22:25], v[6:9], v[222:225], v[18:21]
	v_mfma_f32_16x16x32_bf16 v[18:21], v[180:183], v[200:203], v[240:243]
	s_waitcnt lgkmcnt(0)
	v_mfma_f32_16x16x32_bf16 v[6:9], v[6:9], v[248:251], v[2:5]
	v_mfma_f32_16x16x32_bf16 v[2:5], v[180:183], v[244:247], v[138:141]
	v_mfma_f32_16x16x32_bf16 v[18:21], v[184:187], v[222:225], v[18:21]
	v_mfma_f32_16x16x32_bf16 v[2:5], v[184:187], v[248:251], v[2:5]
	s_setprio 0
	s_setprio 1
	v_mfma_f32_16x16x32_bf16 v[26:29], v[196:199], v[82:85], v[26:29]
	v_mfma_f32_16x16x32_bf16 v[30:33], v[130:133], v[82:85], v[30:33]
	v_mfma_f32_16x16x32_bf16 v[82:85], v[148:151], v[164:167], v[26:29]
	v_mfma_f32_16x16x32_bf16 v[26:29], v[130:133], v[168:171], v[152:155]
	v_mfma_f32_16x16x32_bf16 v[54:57], v[160:163], v[188:191], v[26:29]
	v_mfma_f32_16x16x32_bf16 v[26:29], v[196:199], v[168:171], v[156:159]
	v_mfma_f32_16x16x32_bf16 v[10:13], v[196:199], v[200:203], v[10:13]
	v_mfma_f32_16x16x32_bf16 v[50:53], v[148:151], v[188:191], v[26:29]
	v_mfma_f32_16x16x32_bf16 v[14:17], v[130:133], v[200:203], v[14:17]
	v_mfma_f32_16x16x32_bf16 v[26:29], v[148:151], v[222:225], v[10:13]
	v_mfma_f32_16x16x32_bf16 v[10:13], v[130:133], v[244:247], v[172:175]
	v_mfma_f32_16x16x32_bf16 v[86:89], v[160:163], v[164:167], v[30:33]
	v_mfma_f32_16x16x32_bf16 v[30:33], v[160:163], v[222:225], v[14:17]
	v_mfma_f32_16x16x32_bf16 v[14:17], v[160:163], v[248:251], v[10:13]
	v_mfma_f32_16x16x32_bf16 v[10:13], v[196:199], v[244:247], v[176:179]
	v_mfma_f32_16x16x32_bf16 v[10:13], v[148:151], v[248:251], v[10:13]
	s_setprio 0
	s_movk_i32 s0, 0x100
	v_cmp_gt_u32_e32 vcc, s0, v142
	s_barrier
	s_and_saveexec_b64 s[0:1], vcc
	s_cbranch_execz .LBB0_81
	s_barrier
	s_branch .LBB0_81

.LBB0_180:
	ds_read_b128 v[164:167], v151
	ds_read_b128 v[168:171], v151 offset:1024
	ds_read_b128 v[172:175], v151 offset:2048
	ds_read_b128 v[176:179], v151 offset:3072
	v_lshl_add_u64 v[204:205], v[138:139], 0, s[12:13]
	v_lshl_add_u64 v[228:229], v[204:205], 0, s[60:61]
	s_add_i32 m0, s1, 0xc000
	ds_read_b128 v[180:183], v0
	ds_read_b128 v[184:187], v0 offset:1024
	ds_read_b128 v[188:191], v0 offset:2048
	ds_read_b128 v[192:195], v0 offset:3072
	ds_read_b128 v[196:199], v0 offset:4096
	ds_read_b128 v[200:203], v0 offset:5120
	ds_read_b128 v[222:225], v0 offset:6144
	ds_read_b128 v[232:235], v0 offset:7168
	global_load_lds_dwordx4 v[228:229], off
	v_lshl_add_u64 v[210:211], v[140:141], 0, s[12:13]
	s_add_i32 m0, s1, 0xe000
	v_lshl_add_u64 v[152:153], v[210:211], 0, s[60:61]
	global_load_lds_dwordx4 v[152:153], off
	s_barrier
	s_waitcnt lgkmcnt(0)
	v_mfma_f32_16x16x32_bf16 v[126:129], v[164:167], v[180:183], v[126:129]
	v_mfma_f32_16x16x32_bf16 v[122:125], v[172:175], v[180:183], v[122:125]
	v_mfma_f32_16x16x32_bf16 v[118:121], v[164:167], v[188:191], v[118:121]
	v_mfma_f32_16x16x32_bf16 v[114:117], v[172:175], v[188:191], v[114:117]
	v_mfma_f32_16x16x32_bf16 v[110:113], v[164:167], v[196:199], v[110:113]
	v_mfma_f32_16x16x32_bf16 v[106:109], v[172:175], v[196:199], v[106:109]
	v_mfma_f32_16x16x32_bf16 v[102:105], v[164:167], v[222:225], v[102:105]
	v_mfma_f32_16x16x32_bf16 v[98:101], v[172:175], v[222:225], v[98:101]
	v_mfma_f32_16x16x32_bf16 v[126:129], v[168:171], v[184:187], v[126:129]
	v_mfma_f32_16x16x32_bf16 v[122:125], v[176:179], v[184:187], v[122:125]
	v_mfma_f32_16x16x32_bf16 v[118:121], v[168:171], v[192:195], v[118:121]
	v_mfma_f32_16x16x32_bf16 v[114:117], v[176:179], v[192:195], v[114:117]
	v_mfma_f32_16x16x32_bf16 v[110:113], v[168:171], v[200:203], v[110:113]
	v_mfma_f32_16x16x32_bf16 v[106:109], v[176:179], v[200:203], v[106:109]
	v_mfma_f32_16x16x32_bf16 v[102:105], v[168:171], v[232:235], v[102:105]
	v_mfma_f32_16x16x32_bf16 v[98:101], v[176:179], v[232:235], v[98:101]
	s_barrier
	v_lshl_add_u64 v[216:217], v[134:135], 0, s[12:13]
	s_add_i32 m0, s1, 0xff00
	ds_read_b128 v[236:239], v151 offset:16384
	ds_read_b128 v[240:243], v151 offset:17408
	ds_read_b128 v[244:247], v151 offset:18432
	ds_read_b128 v[248:251], v151 offset:19456
	global_load_lds_dwordx4 v[216:217], off offset:256
	s_add_i32 m0, s1, 0x11f00
	v_lshl_add_u64 v[218:219], v[136:137], 0, s[12:13]
	global_load_lds_dwordx4 v[218:219], off offset:256
	s_barrier
	s_waitcnt lgkmcnt(0)
	v_mfma_f32_16x16x32_bf16 v[94:97], v[236:239], v[180:183], v[94:97]
	v_mfma_f32_16x16x32_bf16 v[90:93], v[244:247], v[180:183], v[90:93]
	v_mfma_f32_16x16x32_bf16 v[86:89], v[236:239], v[188:191], v[86:89]
	v_mfma_f32_16x16x32_bf16 v[82:85], v[244:247], v[188:191], v[82:85]
	v_mfma_f32_16x16x32_bf16 v[78:81], v[236:239], v[196:199], v[78:81]
	v_mfma_f32_16x16x32_bf16 v[74:77], v[244:247], v[196:199], v[74:77]
	v_mfma_f32_16x16x32_bf16 v[70:73], v[236:239], v[222:225], v[70:73]
	v_mfma_f32_16x16x32_bf16 v[66:69], v[244:247], v[222:225], v[66:69]
	v_mfma_f32_16x16x32_bf16 v[94:97], v[240:243], v[184:187], v[94:97]
	v_mfma_f32_16x16x32_bf16 v[90:93], v[248:251], v[184:187], v[90:93]
	v_mfma_f32_16x16x32_bf16 v[86:89], v[240:243], v[192:195], v[86:89]
	v_mfma_f32_16x16x32_bf16 v[82:85], v[248:251], v[192:195], v[82:85]
	v_mfma_f32_16x16x32_bf16 v[78:81], v[240:243], v[200:203], v[78:81]
	v_mfma_f32_16x16x32_bf16 v[74:77], v[248:251], v[200:203], v[74:77]
	v_mfma_f32_16x16x32_bf16 v[70:73], v[240:243], v[232:235], v[70:73]
	v_mfma_f32_16x16x32_bf16 v[66:69], v[248:251], v[232:235], v[66:69]
	v_lshl_add_u64 v[158:159], v[204:205], 0, s[74:75]
	s_mov_b32 m0, s1
	s_barrier
	ds_read_b128 v[180:183], v0 offset:16384
	ds_read_b128 v[184:187], v0 offset:17408
	ds_read_b128 v[188:191], v0 offset:18432
	ds_read_b128 v[192:195], v0 offset:19456
	ds_read_b128 v[196:199], v0 offset:20480
	ds_read_b128 v[200:203], v0 offset:21504
	ds_read_b128 v[222:225], v0 offset:22528
	ds_read_b128 v[232:235], v0 offset:23552
	global_load_lds_dwordx4 v[158:159], off
	s_add_i32 m0, s1, 0x1f00
	s_nop 0
	global_load_lds_dwordx4 v[210:211], off offset:256
	s_barrier
	s_waitcnt lgkmcnt(0)
	v_mfma_f32_16x16x32_bf16 v[62:65], v[164:167], v[180:183], v[62:65]
	v_mfma_f32_16x16x32_bf16 v[58:61], v[172:175], v[180:183], v[58:61]
	v_mfma_f32_16x16x32_bf16 v[54:57], v[164:167], v[188:191], v[54:57]
	v_mfma_f32_16x16x32_bf16 v[50:53], v[172:175], v[188:191], v[50:53]
	v_mfma_f32_16x16x32_bf16 v[46:49], v[164:167], v[196:199], v[46:49]
	v_mfma_f32_16x16x32_bf16 v[42:45], v[172:175], v[196:199], v[42:45]
	v_mfma_f32_16x16x32_bf16 v[38:41], v[164:167], v[222:225], v[38:41]
	v_mfma_f32_16x16x32_bf16 v[34:37], v[172:175], v[222:225], v[34:37]
	v_mfma_f32_16x16x32_bf16 v[62:65], v[168:171], v[184:187], v[62:65]
	v_mfma_f32_16x16x32_bf16 v[58:61], v[176:179], v[184:187], v[58:61]
	v_mfma_f32_16x16x32_bf16 v[54:57], v[168:171], v[192:195], v[54:57]
	v_mfma_f32_16x16x32_bf16 v[50:53], v[176:179], v[192:195], v[50:53]
	v_mfma_f32_16x16x32_bf16 v[46:49], v[168:171], v[200:203], v[46:49]
	v_mfma_f32_16x16x32_bf16 v[42:45], v[176:179], v[200:203], v[42:45]
	v_mfma_f32_16x16x32_bf16 v[38:41], v[168:171], v[232:235], v[38:41]
	v_mfma_f32_16x16x32_bf16 v[34:37], v[176:179], v[232:235], v[34:37]
	s_barrier
	s_add_i32 m0, s1, 0x14000
	v_lshl_add_u64 v[154:155], v[216:217], 0, s[18:19]
	global_load_lds_dwordx4 v[154:155], off
	s_add_i32 m0, s1, 0x16000
	v_lshl_add_u64 v[156:157], v[218:219], 0, s[18:19]
	global_load_lds_dwordx4 v[156:157], off
	s_waitcnt vmcnt(6)
	s_barrier
	v_mfma_f32_16x16x32_bf16 v[30:33], v[236:239], v[180:183], v[30:33]
	v_mfma_f32_16x16x32_bf16 v[26:29], v[244:247], v[180:183], v[26:29]
	v_mfma_f32_16x16x32_bf16 v[22:25], v[236:239], v[188:191], v[22:25]
	v_mfma_f32_16x16x32_bf16 v[18:21], v[244:247], v[188:191], v[18:21]
	v_mfma_f32_16x16x32_bf16 v[14:17], v[236:239], v[196:199], v[14:17]
	v_mfma_f32_16x16x32_bf16 v[10:13], v[244:247], v[196:199], v[10:13]
	v_mfma_f32_16x16x32_bf16 v[6:9], v[236:239], v[222:225], v[6:9]
	v_mfma_f32_16x16x32_bf16 v[2:5], v[244:247], v[222:225], v[2:5]
	v_mfma_f32_16x16x32_bf16 v[30:33], v[240:243], v[184:187], v[30:33]
	v_mfma_f32_16x16x32_bf16 v[26:29], v[248:251], v[184:187], v[26:29]
	v_mfma_f32_16x16x32_bf16 v[22:25], v[240:243], v[192:195], v[22:25]
	v_mfma_f32_16x16x32_bf16 v[18:21], v[248:251], v[192:195], v[18:21]
	v_mfma_f32_16x16x32_bf16 v[14:17], v[240:243], v[200:203], v[14:17]
	v_mfma_f32_16x16x32_bf16 v[10:13], v[248:251], v[200:203], v[10:13]
	v_mfma_f32_16x16x32_bf16 v[6:9], v[240:243], v[232:235], v[6:9]
	v_mfma_f32_16x16x32_bf16 v[2:5], v[248:251], v[232:235], v[2:5]
	s_barrier
	ds_read_b128 v[164:167], v151 offset:32768
	ds_read_b128 v[168:171], v151 offset:33792
	ds_read_b128 v[172:175], v151 offset:34816
	ds_read_b128 v[176:179], v151 offset:35840
	s_add_i32 m0, s1, 0x3f80
	ds_read_b128 v[180:183], v0 offset:32768
	ds_read_b128 v[184:187], v0 offset:33792
	ds_read_b128 v[188:191], v0 offset:34816
	ds_read_b128 v[192:195], v0 offset:35840
	ds_read_b128 v[196:199], v0 offset:36864
	ds_read_b128 v[200:203], v0 offset:37888
	ds_read_b128 v[222:225], v0 offset:38912
	ds_read_b128 v[232:235], v0 offset:39936
	global_load_lds_dwordx4 v[228:229], off offset:128
	s_add_i32 m0, s1, 0x5f80
	s_nop 0
	global_load_lds_dwordx4 v[152:153], off offset:128
	s_barrier
	s_waitcnt lgkmcnt(0)
	v_mfma_f32_16x16x32_bf16 v[126:129], v[164:167], v[180:183], v[126:129]
	v_mfma_f32_16x16x32_bf16 v[122:125], v[172:175], v[180:183], v[122:125]
	v_mfma_f32_16x16x32_bf16 v[118:121], v[164:167], v[188:191], v[118:121]
	v_mfma_f32_16x16x32_bf16 v[114:117], v[172:175], v[188:191], v[114:117]
	v_mfma_f32_16x16x32_bf16 v[110:113], v[164:167], v[196:199], v[110:113]
	v_mfma_f32_16x16x32_bf16 v[106:109], v[172:175], v[196:199], v[106:109]
	v_mfma_f32_16x16x32_bf16 v[102:105], v[164:167], v[222:225], v[102:105]
	v_mfma_f32_16x16x32_bf16 v[98:101], v[172:175], v[222:225], v[98:101]
	v_mfma_f32_16x16x32_bf16 v[126:129], v[168:171], v[184:187], v[126:129]
	v_mfma_f32_16x16x32_bf16 v[122:125], v[176:179], v[184:187], v[122:125]
	v_mfma_f32_16x16x32_bf16 v[118:121], v[168:171], v[192:195], v[118:121]
	v_mfma_f32_16x16x32_bf16 v[114:117], v[176:179], v[192:195], v[114:117]
	v_mfma_f32_16x16x32_bf16 v[110:113], v[168:171], v[200:203], v[110:113]
	v_mfma_f32_16x16x32_bf16 v[106:109], v[176:179], v[200:203], v[106:109]
	v_mfma_f32_16x16x32_bf16 v[102:105], v[168:171], v[232:235], v[102:105]
	v_mfma_f32_16x16x32_bf16 v[98:101], v[176:179], v[232:235], v[98:101]
	s_barrier
	s_add_i32 m0, s1, 0x17e80
	ds_read_b128 v[236:239], v151 offset:49152
	ds_read_b128 v[240:243], v151 offset:50176
	ds_read_b128 v[244:247], v151 offset:51200
	ds_read_b128 v[248:251], v151 offset:52224
	global_load_lds_dwordx4 v[216:217], off offset:384
	s_add_i32 m0, s1, 0x19e80
	s_nop 0
	global_load_lds_dwordx4 v[218:219], off offset:384
	s_barrier
	s_waitcnt lgkmcnt(0)
	v_mfma_f32_16x16x32_bf16 v[94:97], v[236:239], v[180:183], v[94:97]
	v_mfma_f32_16x16x32_bf16 v[90:93], v[244:247], v[180:183], v[90:93]
	v_mfma_f32_16x16x32_bf16 v[86:89], v[236:239], v[188:191], v[86:89]
	v_mfma_f32_16x16x32_bf16 v[82:85], v[244:247], v[188:191], v[82:85]
	v_mfma_f32_16x16x32_bf16 v[78:81], v[236:239], v[196:199], v[78:81]
	v_mfma_f32_16x16x32_bf16 v[74:77], v[244:247], v[196:199], v[74:77]
	v_mfma_f32_16x16x32_bf16 v[70:73], v[236:239], v[222:225], v[70:73]
	v_mfma_f32_16x16x32_bf16 v[66:69], v[244:247], v[222:225], v[66:69]
	v_mfma_f32_16x16x32_bf16 v[94:97], v[240:243], v[184:187], v[94:97]
	v_mfma_f32_16x16x32_bf16 v[90:93], v[248:251], v[184:187], v[90:93]
	v_mfma_f32_16x16x32_bf16 v[86:89], v[240:243], v[192:195], v[86:89]
	v_mfma_f32_16x16x32_bf16 v[82:85], v[248:251], v[192:195], v[82:85]
	v_mfma_f32_16x16x32_bf16 v[78:81], v[240:243], v[200:203], v[78:81]
	v_mfma_f32_16x16x32_bf16 v[74:77], v[248:251], v[200:203], v[74:77]
	v_mfma_f32_16x16x32_bf16 v[70:73], v[240:243], v[232:235], v[70:73]
	v_mfma_f32_16x16x32_bf16 v[66:69], v[248:251], v[232:235], v[66:69]
	s_add_i32 m0, s1, 0x7e80
	s_barrier
	ds_read_b128 v[180:183], v0 offset:49152
	ds_read_b128 v[184:187], v0 offset:50176
	ds_read_b128 v[188:191], v0 offset:51200
	ds_read_b128 v[192:195], v0 offset:52224
	ds_read_b128 v[196:199], v0 offset:53248
	ds_read_b128 v[200:203], v0 offset:54272
	ds_read_b128 v[222:225], v0 offset:55296
	ds_read_b128 v[232:235], v0 offset:56320
	global_load_lds_dwordx4 v[204:205], off offset:384
	s_add_i32 m0, s1, 0x9e80
	s_nop 0
	global_load_lds_dwordx4 v[210:211], off offset:384
	s_barrier
	s_waitcnt lgkmcnt(0)
	v_mfma_f32_16x16x32_bf16 v[62:65], v[164:167], v[180:183], v[62:65]
	v_mfma_f32_16x16x32_bf16 v[58:61], v[172:175], v[180:183], v[58:61]
	v_mfma_f32_16x16x32_bf16 v[54:57], v[164:167], v[188:191], v[54:57]
	v_mfma_f32_16x16x32_bf16 v[50:53], v[172:175], v[188:191], v[50:53]
	v_mfma_f32_16x16x32_bf16 v[46:49], v[164:167], v[196:199], v[46:49]
	v_mfma_f32_16x16x32_bf16 v[42:45], v[172:175], v[196:199], v[42:45]
	v_mfma_f32_16x16x32_bf16 v[38:41], v[164:167], v[222:225], v[38:41]
	v_mfma_f32_16x16x32_bf16 v[34:37], v[172:175], v[222:225], v[34:37]
	v_mfma_f32_16x16x32_bf16 v[62:65], v[168:171], v[184:187], v[62:65]
	v_mfma_f32_16x16x32_bf16 v[58:61], v[176:179], v[184:187], v[58:61]
	v_mfma_f32_16x16x32_bf16 v[54:57], v[168:171], v[192:195], v[54:57]
	v_mfma_f32_16x16x32_bf16 v[50:53], v[176:179], v[192:195], v[50:53]
	v_mfma_f32_16x16x32_bf16 v[46:49], v[168:171], v[200:203], v[46:49]
	v_mfma_f32_16x16x32_bf16 v[42:45], v[176:179], v[200:203], v[42:45]
	v_mfma_f32_16x16x32_bf16 v[38:41], v[168:171], v[232:235], v[38:41]
	v_mfma_f32_16x16x32_bf16 v[34:37], v[176:179], v[232:235], v[34:37]
	s_barrier
	s_add_i32 m0, s1, 0x1bf80
	s_nop 0
	global_load_lds_dwordx4 v[154:155], off offset:128
	s_add_i32 m0, s1, 0x1df80
	s_nop 0
	global_load_lds_dwordx4 v[156:157], off offset:128
	s_waitcnt vmcnt(6)
	s_barrier
	v_mfma_f32_16x16x32_bf16 v[30:33], v[236:239], v[180:183], v[30:33]
	v_mfma_f32_16x16x32_bf16 v[26:29], v[244:247], v[180:183], v[26:29]
	v_mfma_f32_16x16x32_bf16 v[22:25], v[236:239], v[188:191], v[22:25]
	v_mfma_f32_16x16x32_bf16 v[18:21], v[244:247], v[188:191], v[18:21]
	v_mfma_f32_16x16x32_bf16 v[14:17], v[236:239], v[196:199], v[14:17]
	v_mfma_f32_16x16x32_bf16 v[10:13], v[244:247], v[196:199], v[10:13]
	v_mfma_f32_16x16x32_bf16 v[6:9], v[236:239], v[222:225], v[6:9]
	v_mfma_f32_16x16x32_bf16 v[2:5], v[244:247], v[222:225], v[2:5]
	v_mfma_f32_16x16x32_bf16 v[30:33], v[240:243], v[184:187], v[30:33]
	v_mfma_f32_16x16x32_bf16 v[26:29], v[248:251], v[184:187], v[26:29]
	v_mfma_f32_16x16x32_bf16 v[22:25], v[240:243], v[192:195], v[22:25]
	v_mfma_f32_16x16x32_bf16 v[18:21], v[248:251], v[192:195], v[18:21]
	v_mfma_f32_16x16x32_bf16 v[14:17], v[240:243], v[200:203], v[14:17]
	v_mfma_f32_16x16x32_bf16 v[10:13], v[248:251], v[200:203], v[10:13]
	v_mfma_f32_16x16x32_bf16 v[6:9], v[240:243], v[232:235], v[6:9]
	v_mfma_f32_16x16x32_bf16 v[2:5], v[248:251], v[232:235], v[2:5]
	s_add_i32 s0, s0, 2
	s_add_u32 s12, s12, 0x100
	s_addc_u32 s13, s13, 0
	s_cmp_lt_u32 s0, 28
	s_barrier
	s_cbranch_scc1 .LBB0_180
	s_add_i32 s1, s1, 0x1e000
	s_mov_b64 s[12:13], 0xf80
	v_readfirstlane_b32 s0, v162
	v_lshl_add_u64 v[132:133], v[132:133], 0, s[12:13]
	s_mov_b32 m0, s0
	v_readfirstlane_b32 s0, v163
	ds_read_b128 v[134:137], v151
	ds_read_b128 v[138:141], v151 offset:1024
	ds_read_b128 v[152:155], v151 offset:2048
	ds_read_b128 v[156:159], v151 offset:3072
	ds_read_b128 v[164:167], v0
	ds_read_b128 v[168:171], v0 offset:1024
	ds_read_b128 v[172:175], v0 offset:2048
	ds_read_b128 v[176:179], v0 offset:3072
	ds_read_b128 v[180:183], v0 offset:4096
	ds_read_b128 v[184:187], v0 offset:5120
	ds_read_b128 v[188:191], v0 offset:6144
	ds_read_b128 v[192:195], v0 offset:7168
	global_load_lds_dwordx4 v[132:133], off
	v_lshl_add_u64 v[130:131], v[130:131], 0, s[12:13]
	s_mov_b32 m0, s0
	s_nop 0
	global_load_lds_dwordx4 v[130:131], off
	s_barrier
	s_waitcnt lgkmcnt(0)
	s_setprio 1
	s_waitcnt lgkmcnt(0)
	v_mfma_f32_16x16x32_bf16 v[126:129], v[134:137], v[164:167], v[126:129]
	v_mfma_f32_16x16x32_bf16 v[122:125], v[152:155], v[164:167], v[122:125]
	v_mfma_f32_16x16x32_bf16 v[114:117], v[152:155], v[172:175], v[114:117]
	v_mfma_f32_16x16x32_bf16 v[106:109], v[152:155], v[180:183], v[106:109]
	v_mfma_f32_16x16x32_bf16 v[98:101], v[152:155], v[188:191], v[98:101]
	v_mfma_f32_16x16x32_bf16 v[126:129], v[138:141], v[168:171], v[126:129]
	v_mfma_f32_16x16x32_bf16 v[122:125], v[156:159], v[168:171], v[122:125]
	v_mfma_f32_16x16x32_bf16 v[118:121], v[134:137], v[172:175], v[118:121]
	v_mfma_f32_16x16x32_bf16 v[114:117], v[156:159], v[176:179], v[114:117]
	v_mfma_f32_16x16x32_bf16 v[110:113], v[134:137], v[180:183], v[110:113]
	v_mfma_f32_16x16x32_bf16 v[106:109], v[156:159], v[184:187], v[106:109]
	v_mfma_f32_16x16x32_bf16 v[102:105], v[134:137], v[188:191], v[102:105]
	v_mfma_f32_16x16x32_bf16 v[98:101], v[156:159], v[192:195], v[98:101]
	v_mfma_f32_16x16x32_bf16 v[130:133], v[138:141], v[176:179], v[118:121]
	v_mfma_f32_16x16x32_bf16 v[160:163], v[138:141], v[184:187], v[110:113]
	v_mfma_f32_16x16x32_bf16 v[196:199], v[138:141], v[192:195], v[102:105]
	s_setprio 0
	s_barrier
	s_nop 0
	ds_read_b128 v[102:105], v151 offset:16384
	ds_read_b128 v[110:113], v151 offset:17408
	ds_read_b128 v[118:121], v151 offset:18432
	ds_read_b128 v[200:203], v151 offset:19456
	s_barrier
	s_waitcnt lgkmcnt(0)
	s_setprio 1
	s_waitcnt lgkmcnt(1)
	v_mfma_f32_16x16x32_bf16 v[90:93], v[118:121], v[164:167], v[90:93]
	v_mfma_f32_16x16x32_bf16 v[82:85], v[118:121], v[172:175], v[82:85]
	v_mfma_f32_16x16x32_bf16 v[74:77], v[118:121], v[180:183], v[74:77]
	v_mfma_f32_16x16x32_bf16 v[66:69], v[118:121], v[188:191], v[66:69]
	v_mfma_f32_16x16x32_bf16 v[94:97], v[102:105], v[164:167], v[94:97]
	s_waitcnt lgkmcnt(0)
	v_mfma_f32_16x16x32_bf16 v[90:93], v[200:203], v[168:171], v[90:93]
	v_mfma_f32_16x16x32_bf16 v[86:89], v[102:105], v[172:175], v[86:89]
	v_mfma_f32_16x16x32_bf16 v[82:85], v[200:203], v[176:179], v[82:85]
	v_mfma_f32_16x16x32_bf16 v[78:81], v[102:105], v[180:183], v[78:81]
	v_mfma_f32_16x16x32_bf16 v[74:77], v[200:203], v[184:187], v[74:77]
	v_mfma_f32_16x16x32_bf16 v[70:73], v[102:105], v[188:191], v[70:73]
	v_mfma_f32_16x16x32_bf16 v[66:69], v[200:203], v[192:195], v[66:69]
	v_mfma_f32_16x16x32_bf16 v[222:225], v[110:113], v[168:171], v[94:97]
	v_mfma_f32_16x16x32_bf16 v[164:167], v[110:113], v[176:179], v[86:89]
	v_mfma_f32_16x16x32_bf16 v[168:171], v[110:113], v[184:187], v[78:81]
	v_mfma_f32_16x16x32_bf16 v[172:175], v[110:113], v[192:195], v[70:73]
	s_setprio 0
	s_barrier
	s_nop 0
	ds_read_b128 v[70:73], v0 offset:16384
	ds_read_b128 v[78:81], v0 offset:17408
	ds_read_b128 v[86:89], v0 offset:18432
	ds_read_b128 v[94:97], v0 offset:19456
	ds_read_b128 v[176:179], v0 offset:20480
	ds_read_b128 v[180:183], v0 offset:21504
	ds_read_b128 v[184:187], v0 offset:22528
	ds_read_b128 v[188:191], v0 offset:23552
	s_waitcnt vmcnt(4)
	s_barrier
	s_waitcnt lgkmcnt(0)
	s_setprio 1
	s_waitcnt lgkmcnt(7)
	v_mfma_f32_16x16x32_bf16 v[62:65], v[134:137], v[70:73], v[62:65]
	v_mfma_f32_16x16x32_bf16 v[58:61], v[152:155], v[70:73], v[58:61]
	s_waitcnt lgkmcnt(5)
	v_mfma_f32_16x16x32_bf16 v[50:53], v[152:155], v[86:89], v[50:53]
	s_waitcnt lgkmcnt(3)
	v_mfma_f32_16x16x32_bf16 v[42:45], v[152:155], v[176:179], v[42:45]
	s_waitcnt lgkmcnt(1)
	v_mfma_f32_16x16x32_bf16 v[34:37], v[152:155], v[184:187], v[34:37]
	v_mfma_f32_16x16x32_bf16 v[62:65], v[138:141], v[78:81], v[62:65]
	v_mfma_f32_16x16x32_bf16 v[58:61], v[156:159], v[78:81], v[58:61]
	v_mfma_f32_16x16x32_bf16 v[54:57], v[134:137], v[86:89], v[54:57]
	v_mfma_f32_16x16x32_bf16 v[50:53], v[156:159], v[94:97], v[50:53]
	v_mfma_f32_16x16x32_bf16 v[46:49], v[134:137], v[176:179], v[46:49]
	v_mfma_f32_16x16x32_bf16 v[42:45], v[156:159], v[180:183], v[42:45]
	v_mfma_f32_16x16x32_bf16 v[38:41], v[134:137], v[184:187], v[38:41]
	s_waitcnt lgkmcnt(0)
	v_mfma_f32_16x16x32_bf16 v[34:37], v[156:159], v[188:191], v[34:37]
	v_mfma_f32_16x16x32_bf16 v[192:195], v[138:141], v[94:97], v[54:57]
	v_mfma_f32_16x16x32_bf16 v[232:235], v[138:141], v[180:183], v[46:49]
	v_mfma_f32_16x16x32_bf16 v[134:137], v[138:141], v[188:191], v[38:41]
	s_setprio 0
	s_setprio 1
	v_mfma_f32_16x16x32_bf16 v[26:29], v[118:121], v[70:73], v[26:29]
	v_mfma_f32_16x16x32_bf16 v[18:21], v[118:121], v[86:89], v[18:21]
	v_mfma_f32_16x16x32_bf16 v[10:13], v[118:121], v[176:179], v[10:13]
	v_mfma_f32_16x16x32_bf16 v[2:5], v[118:121], v[184:187], v[2:5]
	v_mfma_f32_16x16x32_bf16 v[30:33], v[102:105], v[70:73], v[30:33]
	v_mfma_f32_16x16x32_bf16 v[26:29], v[200:203], v[78:81], v[26:29]
	v_mfma_f32_16x16x32_bf16 v[22:25], v[102:105], v[86:89], v[22:25]
	v_mfma_f32_16x16x32_bf16 v[18:21], v[200:203], v[94:97], v[18:21]
	v_mfma_f32_16x16x32_bf16 v[14:17], v[102:105], v[176:179], v[14:17]
	v_mfma_f32_16x16x32_bf16 v[10:13], v[200:203], v[180:183], v[10:13]
	v_mfma_f32_16x16x32_bf16 v[6:9], v[102:105], v[184:187], v[6:9]
	v_mfma_f32_16x16x32_bf16 v[2:5], v[200:203], v[188:191], v[2:5]
	v_mfma_f32_16x16x32_bf16 v[138:141], v[110:113], v[78:81], v[30:33]
	v_mfma_f32_16x16x32_bf16 v[152:155], v[110:113], v[94:97], v[22:25]
	v_mfma_f32_16x16x32_bf16 v[156:159], v[110:113], v[180:183], v[14:17]
	v_mfma_f32_16x16x32_bf16 v[176:179], v[110:113], v[188:191], v[6:9]
	s_setprio 0
	s_barrier
	s_nop 0
	ds_read_b128 v[6:9], v151 offset:32768
	ds_read_b128 v[14:17], v151 offset:33792
	ds_read_b128 v[180:183], v151 offset:34816
	ds_read_b128 v[184:187], v151 offset:35840
	ds_read_b128 v[22:25], v0 offset:32768
	ds_read_b128 v[30:33], v0 offset:33792
	ds_read_b128 v[38:41], v0 offset:34816
	ds_read_b128 v[46:49], v0 offset:35840
	ds_read_b128 v[54:57], v0 offset:36864
	ds_read_b128 v[188:191], v0 offset:37888
	ds_read_b128 v[200:203], v0 offset:38912
	ds_read_b128 v[236:239], v0 offset:39936
	s_waitcnt vmcnt(2)
	s_barrier
	s_waitcnt lgkmcnt(0)
	s_setprio 1
	s_waitcnt lgkmcnt(7)
	v_mfma_f32_16x16x32_bf16 v[70:73], v[6:9], v[22:25], v[126:129]
	s_waitcnt lgkmcnt(6)
	v_mfma_f32_16x16x32_bf16 v[126:129], v[14:17], v[30:33], v[70:73]
	v_mfma_f32_16x16x32_bf16 v[70:73], v[180:183], v[22:25], v[122:125]
	v_mfma_f32_16x16x32_bf16 v[118:121], v[184:187], v[30:33], v[70:73]
	s_waitcnt lgkmcnt(5)
	v_mfma_f32_16x16x32_bf16 v[70:73], v[6:9], v[38:41], v[130:133]
	s_waitcnt lgkmcnt(4)
	v_mfma_f32_16x16x32_bf16 v[110:113], v[14:17], v[46:49], v[70:73]
	v_mfma_f32_16x16x32_bf16 v[70:73], v[180:183], v[38:41], v[114:117]
	v_mfma_f32_16x16x32_bf16 v[102:105], v[184:187], v[46:49], v[70:73]
	s_waitcnt lgkmcnt(3)
	v_mfma_f32_16x16x32_bf16 v[70:73], v[6:9], v[54:57], v[160:163]
	s_waitcnt lgkmcnt(2)
	v_mfma_f32_16x16x32_bf16 v[94:97], v[14:17], v[188:191], v[70:73]
	v_mfma_f32_16x16x32_bf16 v[70:73], v[180:183], v[54:57], v[106:109]
	v_mfma_f32_16x16x32_bf16 v[86:89], v[184:187], v[188:191], v[70:73]
	s_waitcnt lgkmcnt(1)
	v_mfma_f32_16x16x32_bf16 v[70:73], v[6:9], v[200:203], v[196:199]
	s_waitcnt lgkmcnt(0)
	v_mfma_f32_16x16x32_bf16 v[78:81], v[14:17], v[236:239], v[70:73]
	v_mfma_f32_16x16x32_bf16 v[70:73], v[180:183], v[200:203], v[98:101]
	v_mfma_f32_16x16x32_bf16 v[70:73], v[184:187], v[236:239], v[70:73]
	s_setprio 0
	s_barrier
	ds_read_b128 v[130:133], v151 offset:49152
	ds_read_b128 v[160:163], v151 offset:50176
	ds_read_b128 v[196:199], v151 offset:51200
	ds_read_b128 v[148:151], v151 offset:52224
	s_waitcnt vmcnt(0)
	s_barrier
	s_waitcnt lgkmcnt(0)
	s_setprio 1
	s_waitcnt lgkmcnt(3)
	v_mfma_f32_16x16x32_bf16 v[98:101], v[130:133], v[22:25], v[222:225]
	s_waitcnt lgkmcnt(1)
	v_mfma_f32_16x16x32_bf16 v[22:25], v[196:199], v[22:25], v[90:93]
	s_waitcnt lgkmcnt(0)
	v_mfma_f32_16x16x32_bf16 v[114:117], v[148:151], v[30:33], v[22:25]
	v_mfma_f32_16x16x32_bf16 v[22:25], v[130:133], v[38:41], v[164:167]
	v_mfma_f32_16x16x32_bf16 v[106:109], v[160:163], v[46:49], v[22:25]
	v_mfma_f32_16x16x32_bf16 v[22:25], v[196:199], v[38:41], v[82:85]
	v_mfma_f32_16x16x32_bf16 v[122:125], v[160:163], v[30:33], v[98:101]
	v_mfma_f32_16x16x32_bf16 v[98:101], v[148:151], v[46:49], v[22:25]
	v_mfma_f32_16x16x32_bf16 v[22:25], v[130:133], v[54:57], v[168:171]
	v_mfma_f32_16x16x32_bf16 v[90:93], v[160:163], v[188:191], v[22:25]
	v_mfma_f32_16x16x32_bf16 v[22:25], v[196:199], v[54:57], v[74:77]
	v_mfma_f32_16x16x32_bf16 v[82:85], v[148:151], v[188:191], v[22:25]
	v_mfma_f32_16x16x32_bf16 v[22:25], v[130:133], v[200:203], v[172:175]
	v_mfma_f32_16x16x32_bf16 v[74:77], v[160:163], v[236:239], v[22:25]
	v_mfma_f32_16x16x32_bf16 v[22:25], v[196:199], v[200:203], v[66:69]
	v_mfma_f32_16x16x32_bf16 v[66:69], v[148:151], v[236:239], v[22:25]
	s_setprio 0
	s_barrier
	ds_read_b128 v[164:167], v0 offset:49152
	ds_read_b128 v[168:171], v0 offset:50176
	ds_read_b128 v[172:175], v0 offset:51200
	ds_read_b128 v[188:191], v0 offset:52224
	ds_read_b128 v[200:203], v0 offset:53248
	ds_read_b128 v[222:225], v0 offset:54272
	ds_read_b128 v[236:239], v0 offset:55296
	ds_read_b128 v[240:243], v0 offset:56320
	s_barrier
	s_waitcnt lgkmcnt(0)
	s_setprio 1
	s_waitcnt lgkmcnt(7)
	v_mfma_f32_16x16x32_bf16 v[22:25], v[6:9], v[164:167], v[62:65]
	s_waitcnt lgkmcnt(6)
	v_mfma_f32_16x16x32_bf16 v[62:65], v[14:17], v[168:171], v[22:25]
	v_mfma_f32_16x16x32_bf16 v[22:25], v[180:183], v[164:167], v[58:61]
	v_mfma_f32_16x16x32_bf16 v[54:57], v[184:187], v[168:171], v[22:25]
	s_waitcnt lgkmcnt(5)
	v_mfma_f32_16x16x32_bf16 v[22:25], v[6:9], v[172:175], v[192:195]
	s_waitcnt lgkmcnt(4)
	v_mfma_f32_16x16x32_bf16 v[46:49], v[14:17], v[188:191], v[22:25]
	v_mfma_f32_16x16x32_bf16 v[22:25], v[180:183], v[172:175], v[50:53]
	v_mfma_f32_16x16x32_bf16 v[38:41], v[184:187], v[188:191], v[22:25]
	s_waitcnt lgkmcnt(3)
	v_mfma_f32_16x16x32_bf16 v[22:25], v[6:9], v[200:203], v[232:235]
	s_waitcnt lgkmcnt(1)
	v_mfma_f32_16x16x32_bf16 v[6:9], v[6:9], v[236:239], v[134:137]
	v_mfma_f32_16x16x32_bf16 v[30:33], v[14:17], v[222:225], v[22:25]
	v_mfma_f32_16x16x32_bf16 v[22:25], v[180:183], v[200:203], v[42:45]
	s_waitcnt lgkmcnt(0)
	v_mfma_f32_16x16x32_bf16 v[14:17], v[14:17], v[240:243], v[6:9]
	v_mfma_f32_16x16x32_bf16 v[6:9], v[180:183], v[236:239], v[34:37]
	v_mfma_f32_16x16x32_bf16 v[22:25], v[184:187], v[222:225], v[22:25]
	v_mfma_f32_16x16x32_bf16 v[6:9], v[184:187], v[240:243], v[6:9]
	s_setprio 0
	s_setprio 1
	v_mfma_f32_16x16x32_bf16 v[34:37], v[130:133], v[164:167], v[138:141]
	v_mfma_f32_16x16x32_bf16 v[26:29], v[196:199], v[164:167], v[26:29]
	v_mfma_f32_16x16x32_bf16 v[18:21], v[196:199], v[172:175], v[18:21]
	v_mfma_f32_16x16x32_bf16 v[58:61], v[160:163], v[168:171], v[34:37]
	v_mfma_f32_16x16x32_bf16 v[50:53], v[148:151], v[168:171], v[26:29]
	v_mfma_f32_16x16x32_bf16 v[26:29], v[130:133], v[172:175], v[152:155]
	v_mfma_f32_16x16x32_bf16 v[34:37], v[148:151], v[188:191], v[18:21]
	v_mfma_f32_16x16x32_bf16 v[18:21], v[130:133], v[200:203], v[156:159]
	v_mfma_f32_16x16x32_bf16 v[10:13], v[196:199], v[200:203], v[10:13]
	v_mfma_f32_16x16x32_bf16 v[42:45], v[160:163], v[188:191], v[26:29]
	v_mfma_f32_16x16x32_bf16 v[26:29], v[160:163], v[222:225], v[18:21]
	v_mfma_f32_16x16x32_bf16 v[18:21], v[148:151], v[222:225], v[10:13]
	v_mfma_f32_16x16x32_bf16 v[10:13], v[130:133], v[236:239], v[176:179]
	v_mfma_f32_16x16x32_bf16 v[2:5], v[196:199], v[236:239], v[2:5]
	v_mfma_f32_16x16x32_bf16 v[10:13], v[160:163], v[240:243], v[10:13]
	v_mfma_f32_16x16x32_bf16 v[2:5], v[148:151], v[240:243], v[2:5]
	s_setprio 0
	s_movk_i32 s0, 0x100
	v_cmp_gt_u32_e32 vcc, s0, v142
	s_barrier
	s_and_saveexec_b64 s[0:1], vcc
	s_cbranch_execz .LBB0_183
	s_barrier

.LBB0_678:
	ds_read_b128 v[164:167], v151
	ds_read_b128 v[168:171], v151 offset:1024
	ds_read_b128 v[172:175], v151 offset:2048
	ds_read_b128 v[176:179], v151 offset:3072
	v_lshl_add_u64 v[204:205], v[138:139], 0, s[8:9]
	v_lshl_add_u64 v[218:219], v[204:205], 0, s[60:61]
	s_add_i32 m0, s1, 0xc000
	ds_read_b128 v[180:183], v0
	ds_read_b128 v[184:187], v0 offset:1024
	ds_read_b128 v[188:191], v0 offset:2048
	ds_read_b128 v[192:195], v0 offset:3072
	ds_read_b128 v[196:199], v0 offset:4096
	ds_read_b128 v[200:203], v0 offset:5120
	ds_read_b128 v[232:235], v0 offset:6144
	ds_read_b128 v[236:239], v0 offset:7168
	global_load_lds_dwordx4 v[218:219], off
	v_lshl_add_u64 v[216:217], v[140:141], 0, s[8:9]
	s_add_i32 m0, s1, 0xe000
	v_lshl_add_u64 v[152:153], v[216:217], 0, s[60:61]
	global_load_lds_dwordx4 v[152:153], off
	s_barrier
	s_waitcnt lgkmcnt(0)
	v_mfma_f32_16x16x32_bf16 v[126:129], v[164:167], v[180:183], v[126:129]
	v_mfma_f32_16x16x32_bf16 v[122:125], v[172:175], v[180:183], v[122:125]
	v_mfma_f32_16x16x32_bf16 v[118:121], v[164:167], v[188:191], v[118:121]
	v_mfma_f32_16x16x32_bf16 v[114:117], v[172:175], v[188:191], v[114:117]
	v_mfma_f32_16x16x32_bf16 v[110:113], v[164:167], v[196:199], v[110:113]
	v_mfma_f32_16x16x32_bf16 v[106:109], v[172:175], v[196:199], v[106:109]
	v_mfma_f32_16x16x32_bf16 v[102:105], v[164:167], v[232:235], v[102:105]
	v_mfma_f32_16x16x32_bf16 v[98:101], v[172:175], v[232:235], v[98:101]
	v_mfma_f32_16x16x32_bf16 v[126:129], v[168:171], v[184:187], v[126:129]
	v_mfma_f32_16x16x32_bf16 v[122:125], v[176:179], v[184:187], v[122:125]
	v_mfma_f32_16x16x32_bf16 v[118:121], v[168:171], v[192:195], v[118:121]
	v_mfma_f32_16x16x32_bf16 v[114:117], v[176:179], v[192:195], v[114:117]
	v_mfma_f32_16x16x32_bf16 v[110:113], v[168:171], v[200:203], v[110:113]
	v_mfma_f32_16x16x32_bf16 v[106:109], v[176:179], v[200:203], v[106:109]
	v_mfma_f32_16x16x32_bf16 v[102:105], v[168:171], v[236:239], v[102:105]
	v_mfma_f32_16x16x32_bf16 v[98:101], v[176:179], v[236:239], v[98:101]
	s_barrier
	v_lshl_add_u64 v[210:211], v[134:135], 0, s[8:9]
	s_add_i32 m0, s1, 0xff00
	ds_read_b128 v[240:243], v151 offset:16384
	ds_read_b128 v[244:247], v151 offset:17408
	ds_read_b128 v[248:251], v151 offset:18432
	ds_read_b128 v[222:225], v151 offset:19456
	global_load_lds_dwordx4 v[210:211], off offset:256
	s_add_i32 m0, s1, 0x11f00
	v_lshl_add_u64 v[228:229], v[136:137], 0, s[8:9]
	global_load_lds_dwordx4 v[228:229], off offset:256
	s_barrier
	s_waitcnt lgkmcnt(0)
	v_mfma_f32_16x16x32_bf16 v[94:97], v[240:243], v[180:183], v[94:97]
	v_mfma_f32_16x16x32_bf16 v[90:93], v[248:251], v[180:183], v[90:93]
	v_mfma_f32_16x16x32_bf16 v[86:89], v[240:243], v[188:191], v[86:89]
	v_mfma_f32_16x16x32_bf16 v[82:85], v[248:251], v[188:191], v[82:85]
	v_mfma_f32_16x16x32_bf16 v[78:81], v[240:243], v[196:199], v[78:81]
	v_mfma_f32_16x16x32_bf16 v[74:77], v[248:251], v[196:199], v[74:77]
	v_mfma_f32_16x16x32_bf16 v[70:73], v[240:243], v[232:235], v[70:73]
	v_mfma_f32_16x16x32_bf16 v[66:69], v[248:251], v[232:235], v[66:69]
	v_mfma_f32_16x16x32_bf16 v[94:97], v[244:247], v[184:187], v[94:97]
	v_mfma_f32_16x16x32_bf16 v[90:93], v[222:225], v[184:187], v[90:93]
	v_mfma_f32_16x16x32_bf16 v[86:89], v[244:247], v[192:195], v[86:89]
	v_mfma_f32_16x16x32_bf16 v[82:85], v[222:225], v[192:195], v[82:85]
	v_mfma_f32_16x16x32_bf16 v[78:81], v[244:247], v[200:203], v[78:81]
	v_mfma_f32_16x16x32_bf16 v[74:77], v[222:225], v[200:203], v[74:77]
	v_mfma_f32_16x16x32_bf16 v[70:73], v[244:247], v[236:239], v[70:73]
	v_mfma_f32_16x16x32_bf16 v[66:69], v[222:225], v[236:239], v[66:69]
	v_lshl_add_u64 v[158:159], v[204:205], 0, s[74:75]
	s_mov_b32 m0, s1
	s_barrier
	ds_read_b128 v[180:183], v0 offset:16384
	ds_read_b128 v[184:187], v0 offset:17408
	ds_read_b128 v[188:191], v0 offset:18432
	ds_read_b128 v[192:195], v0 offset:19456
	ds_read_b128 v[196:199], v0 offset:20480
	ds_read_b128 v[200:203], v0 offset:21504
	ds_read_b128 v[232:235], v0 offset:22528
	ds_read_b128 v[236:239], v0 offset:23552
	global_load_lds_dwordx4 v[158:159], off
	s_add_i32 m0, s1, 0x1f00
	s_nop 0
	global_load_lds_dwordx4 v[216:217], off offset:256
	s_barrier
	s_waitcnt lgkmcnt(0)
	v_mfma_f32_16x16x32_bf16 v[62:65], v[164:167], v[180:183], v[62:65]
	v_mfma_f32_16x16x32_bf16 v[58:61], v[172:175], v[180:183], v[58:61]
	v_mfma_f32_16x16x32_bf16 v[54:57], v[164:167], v[188:191], v[54:57]
	v_mfma_f32_16x16x32_bf16 v[50:53], v[172:175], v[188:191], v[50:53]
	v_mfma_f32_16x16x32_bf16 v[46:49], v[164:167], v[196:199], v[46:49]
	v_mfma_f32_16x16x32_bf16 v[42:45], v[172:175], v[196:199], v[42:45]
	v_mfma_f32_16x16x32_bf16 v[38:41], v[164:167], v[232:235], v[38:41]
	v_mfma_f32_16x16x32_bf16 v[34:37], v[172:175], v[232:235], v[34:37]
	v_mfma_f32_16x16x32_bf16 v[62:65], v[168:171], v[184:187], v[62:65]
	v_mfma_f32_16x16x32_bf16 v[58:61], v[176:179], v[184:187], v[58:61]
	v_mfma_f32_16x16x32_bf16 v[54:57], v[168:171], v[192:195], v[54:57]
	v_mfma_f32_16x16x32_bf16 v[50:53], v[176:179], v[192:195], v[50:53]
	v_mfma_f32_16x16x32_bf16 v[46:49], v[168:171], v[200:203], v[46:49]
	v_mfma_f32_16x16x32_bf16 v[42:45], v[176:179], v[200:203], v[42:45]
	v_mfma_f32_16x16x32_bf16 v[38:41], v[168:171], v[236:239], v[38:41]
	v_mfma_f32_16x16x32_bf16 v[34:37], v[176:179], v[236:239], v[34:37]
	s_barrier
	s_add_i32 m0, s1, 0x14000
	v_lshl_add_u64 v[154:155], v[210:211], 0, s[18:19]
	global_load_lds_dwordx4 v[154:155], off
	s_add_i32 m0, s1, 0x16000
	v_lshl_add_u64 v[156:157], v[228:229], 0, s[18:19]
	global_load_lds_dwordx4 v[156:157], off
	s_waitcnt vmcnt(6)
	s_barrier
	v_mfma_f32_16x16x32_bf16 v[30:33], v[240:243], v[180:183], v[30:33]
	v_mfma_f32_16x16x32_bf16 v[26:29], v[248:251], v[180:183], v[26:29]
	v_mfma_f32_16x16x32_bf16 v[22:25], v[240:243], v[188:191], v[22:25]
	v_mfma_f32_16x16x32_bf16 v[18:21], v[248:251], v[188:191], v[18:21]
	v_mfma_f32_16x16x32_bf16 v[14:17], v[240:243], v[196:199], v[14:17]
	v_mfma_f32_16x16x32_bf16 v[10:13], v[248:251], v[196:199], v[10:13]
	v_mfma_f32_16x16x32_bf16 v[6:9], v[240:243], v[232:235], v[6:9]
	v_mfma_f32_16x16x32_bf16 v[2:5], v[248:251], v[232:235], v[2:5]
	v_mfma_f32_16x16x32_bf16 v[30:33], v[244:247], v[184:187], v[30:33]
	v_mfma_f32_16x16x32_bf16 v[26:29], v[222:225], v[184:187], v[26:29]
	v_mfma_f32_16x16x32_bf16 v[22:25], v[244:247], v[192:195], v[22:25]
	v_mfma_f32_16x16x32_bf16 v[18:21], v[222:225], v[192:195], v[18:21]
	v_mfma_f32_16x16x32_bf16 v[14:17], v[244:247], v[200:203], v[14:17]
	v_mfma_f32_16x16x32_bf16 v[10:13], v[222:225], v[200:203], v[10:13]
	v_mfma_f32_16x16x32_bf16 v[6:9], v[244:247], v[236:239], v[6:9]
	v_mfma_f32_16x16x32_bf16 v[2:5], v[222:225], v[236:239], v[2:5]
	s_barrier
	ds_read_b128 v[164:167], v151 offset:32768
	ds_read_b128 v[168:171], v151 offset:33792
	ds_read_b128 v[172:175], v151 offset:34816
	ds_read_b128 v[176:179], v151 offset:35840
	s_add_i32 m0, s1, 0x3f80
	ds_read_b128 v[180:183], v0 offset:32768
	ds_read_b128 v[184:187], v0 offset:33792
	ds_read_b128 v[188:191], v0 offset:34816
	ds_read_b128 v[192:195], v0 offset:35840
	ds_read_b128 v[196:199], v0 offset:36864
	ds_read_b128 v[200:203], v0 offset:37888
	ds_read_b128 v[222:225], v0 offset:38912
	ds_read_b128 v[232:235], v0 offset:39936
	global_load_lds_dwordx4 v[218:219], off offset:128
	s_add_i32 m0, s1, 0x5f80
	s_nop 0
	global_load_lds_dwordx4 v[152:153], off offset:128
	s_barrier
	s_waitcnt lgkmcnt(0)
	v_mfma_f32_16x16x32_bf16 v[126:129], v[164:167], v[180:183], v[126:129]
	v_mfma_f32_16x16x32_bf16 v[122:125], v[172:175], v[180:183], v[122:125]
	v_mfma_f32_16x16x32_bf16 v[118:121], v[164:167], v[188:191], v[118:121]
	v_mfma_f32_16x16x32_bf16 v[114:117], v[172:175], v[188:191], v[114:117]
	v_mfma_f32_16x16x32_bf16 v[110:113], v[164:167], v[196:199], v[110:113]
	v_mfma_f32_16x16x32_bf16 v[106:109], v[172:175], v[196:199], v[106:109]
	v_mfma_f32_16x16x32_bf16 v[102:105], v[164:167], v[222:225], v[102:105]
	v_mfma_f32_16x16x32_bf16 v[98:101], v[172:175], v[222:225], v[98:101]
	v_mfma_f32_16x16x32_bf16 v[126:129], v[168:171], v[184:187], v[126:129]
	v_mfma_f32_16x16x32_bf16 v[122:125], v[176:179], v[184:187], v[122:125]
	v_mfma_f32_16x16x32_bf16 v[118:121], v[168:171], v[192:195], v[118:121]
	v_mfma_f32_16x16x32_bf16 v[114:117], v[176:179], v[192:195], v[114:117]
	v_mfma_f32_16x16x32_bf16 v[110:113], v[168:171], v[200:203], v[110:113]
	v_mfma_f32_16x16x32_bf16 v[106:109], v[176:179], v[200:203], v[106:109]
	v_mfma_f32_16x16x32_bf16 v[102:105], v[168:171], v[232:235], v[102:105]
	v_mfma_f32_16x16x32_bf16 v[98:101], v[176:179], v[232:235], v[98:101]
	s_barrier
	s_add_i32 m0, s1, 0x17e80
	ds_read_b128 v[236:239], v151 offset:49152
	ds_read_b128 v[240:243], v151 offset:50176
	ds_read_b128 v[244:247], v151 offset:51200
	ds_read_b128 v[248:251], v151 offset:52224
	global_load_lds_dwordx4 v[210:211], off offset:384
	s_add_i32 m0, s1, 0x19e80
	s_nop 0
	global_load_lds_dwordx4 v[228:229], off offset:384
	s_barrier
	s_waitcnt lgkmcnt(0)
	v_mfma_f32_16x16x32_bf16 v[94:97], v[236:239], v[180:183], v[94:97]
	v_mfma_f32_16x16x32_bf16 v[90:93], v[244:247], v[180:183], v[90:93]
	v_mfma_f32_16x16x32_bf16 v[86:89], v[236:239], v[188:191], v[86:89]
	v_mfma_f32_16x16x32_bf16 v[82:85], v[244:247], v[188:191], v[82:85]
	v_mfma_f32_16x16x32_bf16 v[78:81], v[236:239], v[196:199], v[78:81]
	v_mfma_f32_16x16x32_bf16 v[74:77], v[244:247], v[196:199], v[74:77]
	v_mfma_f32_16x16x32_bf16 v[70:73], v[236:239], v[222:225], v[70:73]
	v_mfma_f32_16x16x32_bf16 v[66:69], v[244:247], v[222:225], v[66:69]
	v_mfma_f32_16x16x32_bf16 v[94:97], v[240:243], v[184:187], v[94:97]
	v_mfma_f32_16x16x32_bf16 v[90:93], v[248:251], v[184:187], v[90:93]
	v_mfma_f32_16x16x32_bf16 v[86:89], v[240:243], v[192:195], v[86:89]
	v_mfma_f32_16x16x32_bf16 v[82:85], v[248:251], v[192:195], v[82:85]
	v_mfma_f32_16x16x32_bf16 v[78:81], v[240:243], v[200:203], v[78:81]
	v_mfma_f32_16x16x32_bf16 v[74:77], v[248:251], v[200:203], v[74:77]
	v_mfma_f32_16x16x32_bf16 v[70:73], v[240:243], v[232:235], v[70:73]
	v_mfma_f32_16x16x32_bf16 v[66:69], v[248:251], v[232:235], v[66:69]
	s_add_i32 m0, s1, 0x7e80
	s_barrier
	ds_read_b128 v[180:183], v0 offset:49152
	ds_read_b128 v[184:187], v0 offset:50176
	ds_read_b128 v[188:191], v0 offset:51200
	ds_read_b128 v[192:195], v0 offset:52224
	ds_read_b128 v[196:199], v0 offset:53248
	ds_read_b128 v[200:203], v0 offset:54272
	ds_read_b128 v[222:225], v0 offset:55296
	ds_read_b128 v[232:235], v0 offset:56320
	global_load_lds_dwordx4 v[204:205], off offset:384
	s_add_i32 m0, s1, 0x9e80
	s_nop 0
	global_load_lds_dwordx4 v[216:217], off offset:384
	s_barrier
	s_waitcnt lgkmcnt(0)
	v_mfma_f32_16x16x32_bf16 v[62:65], v[164:167], v[180:183], v[62:65]
	v_mfma_f32_16x16x32_bf16 v[58:61], v[172:175], v[180:183], v[58:61]
	v_mfma_f32_16x16x32_bf16 v[54:57], v[164:167], v[188:191], v[54:57]
	v_mfma_f32_16x16x32_bf16 v[50:53], v[172:175], v[188:191], v[50:53]
	v_mfma_f32_16x16x32_bf16 v[46:49], v[164:167], v[196:199], v[46:49]
	v_mfma_f32_16x16x32_bf16 v[42:45], v[172:175], v[196:199], v[42:45]
	v_mfma_f32_16x16x32_bf16 v[38:41], v[164:167], v[222:225], v[38:41]
	v_mfma_f32_16x16x32_bf16 v[34:37], v[172:175], v[222:225], v[34:37]
	v_mfma_f32_16x16x32_bf16 v[62:65], v[168:171], v[184:187], v[62:65]
	v_mfma_f32_16x16x32_bf16 v[58:61], v[176:179], v[184:187], v[58:61]
	v_mfma_f32_16x16x32_bf16 v[54:57], v[168:171], v[192:195], v[54:57]
	v_mfma_f32_16x16x32_bf16 v[50:53], v[176:179], v[192:195], v[50:53]
	v_mfma_f32_16x16x32_bf16 v[46:49], v[168:171], v[200:203], v[46:49]
	v_mfma_f32_16x16x32_bf16 v[42:45], v[176:179], v[200:203], v[42:45]
	v_mfma_f32_16x16x32_bf16 v[38:41], v[168:171], v[232:235], v[38:41]
	v_mfma_f32_16x16x32_bf16 v[34:37], v[176:179], v[232:235], v[34:37]
	s_barrier
	s_add_i32 m0, s1, 0x1bf80
	s_nop 0
	global_load_lds_dwordx4 v[154:155], off offset:128
	s_add_i32 m0, s1, 0x1df80
	s_nop 0
	global_load_lds_dwordx4 v[156:157], off offset:128
	s_waitcnt vmcnt(6)
	s_barrier
	v_mfma_f32_16x16x32_bf16 v[30:33], v[236:239], v[180:183], v[30:33]
	v_mfma_f32_16x16x32_bf16 v[26:29], v[244:247], v[180:183], v[26:29]
	v_mfma_f32_16x16x32_bf16 v[22:25], v[236:239], v[188:191], v[22:25]
	v_mfma_f32_16x16x32_bf16 v[18:21], v[244:247], v[188:191], v[18:21]
	v_mfma_f32_16x16x32_bf16 v[14:17], v[236:239], v[196:199], v[14:17]
	v_mfma_f32_16x16x32_bf16 v[10:13], v[244:247], v[196:199], v[10:13]
	v_mfma_f32_16x16x32_bf16 v[6:9], v[236:239], v[222:225], v[6:9]
	v_mfma_f32_16x16x32_bf16 v[2:5], v[244:247], v[222:225], v[2:5]
	v_mfma_f32_16x16x32_bf16 v[30:33], v[240:243], v[184:187], v[30:33]
	v_mfma_f32_16x16x32_bf16 v[26:29], v[248:251], v[184:187], v[26:29]
	v_mfma_f32_16x16x32_bf16 v[22:25], v[240:243], v[192:195], v[22:25]
	v_mfma_f32_16x16x32_bf16 v[18:21], v[248:251], v[192:195], v[18:21]
	v_mfma_f32_16x16x32_bf16 v[14:17], v[240:243], v[200:203], v[14:17]
	v_mfma_f32_16x16x32_bf16 v[10:13], v[248:251], v[200:203], v[10:13]
	v_mfma_f32_16x16x32_bf16 v[6:9], v[240:243], v[232:235], v[6:9]
	v_mfma_f32_16x16x32_bf16 v[2:5], v[248:251], v[232:235], v[2:5]
	s_add_i32 s0, s0, 2
	s_add_u32 s8, s8, 0x100
	s_addc_u32 s9, s9, 0
	s_cmp_lt_u32 s0, 28
	s_barrier
	s_cbranch_scc1 .LBB0_678
	s_add_i32 s1, s1, 0x1e000
	s_mov_b64 s[8:9], 0xf80
	v_readfirstlane_b32 s0, v162
	v_lshl_add_u64 v[132:133], v[132:133], 0, s[8:9]
	s_mov_b32 m0, s0
	v_readfirstlane_b32 s0, v163
	ds_read_b128 v[134:137], v151
	ds_read_b128 v[138:141], v151 offset:1024
	ds_read_b128 v[152:155], v151 offset:2048
	ds_read_b128 v[156:159], v151 offset:3072
	ds_read_b128 v[164:167], v0
	ds_read_b128 v[168:171], v0 offset:1024
	ds_read_b128 v[172:175], v0 offset:2048
	ds_read_b128 v[176:179], v0 offset:3072
	ds_read_b128 v[180:183], v0 offset:4096
	ds_read_b128 v[184:187], v0 offset:5120
	ds_read_b128 v[188:191], v0 offset:6144
	ds_read_b128 v[192:195], v0 offset:7168
	global_load_lds_dwordx4 v[132:133], off
	v_lshl_add_u64 v[130:131], v[130:131], 0, s[8:9]
	s_mov_b32 m0, s0
	s_nop 0
	global_load_lds_dwordx4 v[130:131], off
	s_barrier
	s_waitcnt lgkmcnt(0)
	s_setprio 1
	s_waitcnt lgkmcnt(0)
	v_mfma_f32_16x16x32_bf16 v[126:129], v[134:137], v[164:167], v[126:129]
	v_mfma_f32_16x16x32_bf16 v[122:125], v[152:155], v[164:167], v[122:125]
	v_mfma_f32_16x16x32_bf16 v[114:117], v[152:155], v[172:175], v[114:117]
	v_mfma_f32_16x16x32_bf16 v[106:109], v[152:155], v[180:183], v[106:109]
	v_mfma_f32_16x16x32_bf16 v[98:101], v[152:155], v[188:191], v[98:101]
	v_mfma_f32_16x16x32_bf16 v[126:129], v[138:141], v[168:171], v[126:129]
	v_mfma_f32_16x16x32_bf16 v[122:125], v[156:159], v[168:171], v[122:125]
	v_mfma_f32_16x16x32_bf16 v[118:121], v[134:137], v[172:175], v[118:121]
	v_mfma_f32_16x16x32_bf16 v[114:117], v[156:159], v[176:179], v[114:117]
	v_mfma_f32_16x16x32_bf16 v[110:113], v[134:137], v[180:183], v[110:113]
	v_mfma_f32_16x16x32_bf16 v[106:109], v[156:159], v[184:187], v[106:109]
	v_mfma_f32_16x16x32_bf16 v[102:105], v[134:137], v[188:191], v[102:105]
	v_mfma_f32_16x16x32_bf16 v[98:101], v[156:159], v[192:195], v[98:101]
	v_mfma_f32_16x16x32_bf16 v[130:133], v[138:141], v[176:179], v[118:121]
	v_mfma_f32_16x16x32_bf16 v[160:163], v[138:141], v[184:187], v[110:113]
	v_mfma_f32_16x16x32_bf16 v[196:199], v[138:141], v[192:195], v[102:105]
	s_setprio 0
	s_barrier
	s_nop 0
	ds_read_b128 v[102:105], v151 offset:16384
	ds_read_b128 v[110:113], v151 offset:17408
	ds_read_b128 v[118:121], v151 offset:18432
	ds_read_b128 v[200:203], v151 offset:19456
	s_barrier
	s_waitcnt lgkmcnt(0)
	s_setprio 1
	s_waitcnt lgkmcnt(1)
	v_mfma_f32_16x16x32_bf16 v[90:93], v[118:121], v[164:167], v[90:93]
	v_mfma_f32_16x16x32_bf16 v[86:89], v[102:105], v[172:175], v[86:89]
	v_mfma_f32_16x16x32_bf16 v[82:85], v[118:121], v[172:175], v[82:85]
	v_mfma_f32_16x16x32_bf16 v[78:81], v[102:105], v[180:183], v[78:81]
	v_mfma_f32_16x16x32_bf16 v[70:73], v[102:105], v[188:191], v[70:73]
	v_mfma_f32_16x16x32_bf16 v[94:97], v[102:105], v[164:167], v[94:97]
	s_waitcnt lgkmcnt(0)
	v_mfma_f32_16x16x32_bf16 v[90:93], v[200:203], v[168:171], v[90:93]
	v_mfma_f32_16x16x32_bf16 v[86:89], v[110:113], v[176:179], v[86:89]
	v_mfma_f32_16x16x32_bf16 v[82:85], v[200:203], v[176:179], v[82:85]
	v_mfma_f32_16x16x32_bf16 v[78:81], v[110:113], v[184:187], v[78:81]
	v_mfma_f32_16x16x32_bf16 v[74:77], v[118:121], v[180:183], v[74:77]
	v_mfma_f32_16x16x32_bf16 v[70:73], v[110:113], v[192:195], v[70:73]
	v_mfma_f32_16x16x32_bf16 v[66:69], v[118:121], v[188:191], v[66:69]
	v_mfma_f32_16x16x32_bf16 v[222:225], v[110:113], v[168:171], v[94:97]
	v_mfma_f32_16x16x32_bf16 v[164:167], v[200:203], v[184:187], v[74:77]
	v_mfma_f32_16x16x32_bf16 v[168:171], v[200:203], v[192:195], v[66:69]
	s_setprio 0
	s_barrier
	s_nop 2
	ds_read_b128 v[66:69], v0 offset:16384
	ds_read_b128 v[74:77], v0 offset:17408
	ds_read_b128 v[94:97], v0 offset:18432
	ds_read_b128 v[172:175], v0 offset:19456
	ds_read_b128 v[176:179], v0 offset:20480
	ds_read_b128 v[180:183], v0 offset:21504
	ds_read_b128 v[184:187], v0 offset:22528
	ds_read_b128 v[188:191], v0 offset:23552
	s_waitcnt vmcnt(4)
	s_barrier
	s_waitcnt lgkmcnt(0)
	s_setprio 1
	s_waitcnt lgkmcnt(5)
	v_mfma_f32_16x16x32_bf16 v[54:57], v[134:137], v[94:97], v[54:57]
	v_mfma_f32_16x16x32_bf16 v[50:53], v[152:155], v[94:97], v[50:53]
	v_mfma_f32_16x16x32_bf16 v[62:65], v[134:137], v[66:69], v[62:65]
	v_mfma_f32_16x16x32_bf16 v[58:61], v[152:155], v[66:69], v[58:61]
	s_waitcnt lgkmcnt(4)
	v_mfma_f32_16x16x32_bf16 v[54:57], v[138:141], v[172:175], v[54:57]
	v_mfma_f32_16x16x32_bf16 v[50:53], v[156:159], v[172:175], v[50:53]
	s_waitcnt lgkmcnt(3)
	v_mfma_f32_16x16x32_bf16 v[46:49], v[134:137], v[176:179], v[46:49]
	v_mfma_f32_16x16x32_bf16 v[42:45], v[152:155], v[176:179], v[42:45]
	s_waitcnt lgkmcnt(1)
	v_mfma_f32_16x16x32_bf16 v[38:41], v[134:137], v[184:187], v[38:41]
	v_mfma_f32_16x16x32_bf16 v[34:37], v[152:155], v[184:187], v[34:37]
	v_mfma_f32_16x16x32_bf16 v[192:195], v[138:141], v[74:77], v[62:65]
	v_mfma_f32_16x16x32_bf16 v[232:235], v[156:159], v[74:77], v[58:61]
	v_mfma_f32_16x16x32_bf16 v[236:239], v[138:141], v[180:183], v[46:49]
	v_mfma_f32_16x16x32_bf16 v[240:243], v[156:159], v[180:183], v[42:45]
	s_waitcnt lgkmcnt(0)
	v_mfma_f32_16x16x32_bf16 v[134:137], v[138:141], v[188:191], v[38:41]
	v_mfma_f32_16x16x32_bf16 v[138:141], v[156:159], v[188:191], v[34:37]
	s_setprio 0
	s_setprio 1
	v_mfma_f32_16x16x32_bf16 v[30:33], v[102:105], v[66:69], v[30:33]
	v_mfma_f32_16x16x32_bf16 v[26:29], v[118:121], v[66:69], v[26:29]
	v_mfma_f32_16x16x32_bf16 v[14:17], v[102:105], v[176:179], v[14:17]
	v_mfma_f32_16x16x32_bf16 v[10:13], v[118:121], v[176:179], v[10:13]
	v_mfma_f32_16x16x32_bf16 v[30:33], v[110:113], v[74:77], v[30:33]
	v_mfma_f32_16x16x32_bf16 v[26:29], v[200:203], v[74:77], v[26:29]
	v_mfma_f32_16x16x32_bf16 v[22:25], v[102:105], v[94:97], v[22:25]
	v_mfma_f32_16x16x32_bf16 v[18:21], v[118:121], v[94:97], v[18:21]
	v_mfma_f32_16x16x32_bf16 v[14:17], v[110:113], v[180:183], v[14:17]
	v_mfma_f32_16x16x32_bf16 v[10:13], v[200:203], v[180:183], v[10:13]
	v_mfma_f32_16x16x32_bf16 v[6:9], v[102:105], v[184:187], v[6:9]
	v_mfma_f32_16x16x32_bf16 v[2:5], v[118:121], v[184:187], v[2:5]
	v_mfma_f32_16x16x32_bf16 v[152:155], v[110:113], v[172:175], v[22:25]
	v_mfma_f32_16x16x32_bf16 v[156:159], v[200:203], v[172:175], v[18:21]
	v_mfma_f32_16x16x32_bf16 v[172:175], v[110:113], v[188:191], v[6:9]
	v_mfma_f32_16x16x32_bf16 v[176:179], v[200:203], v[188:191], v[2:5]
	s_setprio 0
	s_barrier
	s_nop 1
	ds_read_b128 v[2:5], v151 offset:32768
	ds_read_b128 v[6:9], v151 offset:33792
	ds_read_b128 v[180:183], v151 offset:34816
	ds_read_b128 v[184:187], v151 offset:35840
	ds_read_b128 v[18:21], v0 offset:32768
	ds_read_b128 v[22:25], v0 offset:33792
	ds_read_b128 v[38:41], v0 offset:34816
	ds_read_b128 v[46:49], v0 offset:35840
	ds_read_b128 v[58:61], v0 offset:36864
	ds_read_b128 v[66:69], v0 offset:37888
	ds_read_b128 v[188:191], v0 offset:38912
	ds_read_b128 v[200:203], v0 offset:39936
	s_waitcnt vmcnt(2)
	s_barrier
	s_waitcnt lgkmcnt(0)
	s_setprio 1
	s_waitcnt lgkmcnt(7)
	v_mfma_f32_16x16x32_bf16 v[34:37], v[2:5], v[18:21], v[126:129]
	s_waitcnt lgkmcnt(6)
	v_mfma_f32_16x16x32_bf16 v[118:121], v[6:9], v[22:25], v[34:37]
	v_mfma_f32_16x16x32_bf16 v[34:37], v[180:183], v[18:21], v[122:125]
	v_mfma_f32_16x16x32_bf16 v[110:113], v[184:187], v[22:25], v[34:37]
	s_waitcnt lgkmcnt(5)
	v_mfma_f32_16x16x32_bf16 v[34:37], v[2:5], v[38:41], v[130:133]
	s_waitcnt lgkmcnt(4)
	v_mfma_f32_16x16x32_bf16 v[102:105], v[6:9], v[46:49], v[34:37]
	v_mfma_f32_16x16x32_bf16 v[34:37], v[180:183], v[38:41], v[114:117]
	v_mfma_f32_16x16x32_bf16 v[94:97], v[184:187], v[46:49], v[34:37]
	s_waitcnt lgkmcnt(3)
	v_mfma_f32_16x16x32_bf16 v[34:37], v[2:5], v[58:61], v[160:163]
	s_waitcnt lgkmcnt(2)
	v_mfma_f32_16x16x32_bf16 v[74:77], v[6:9], v[66:69], v[34:37]
	v_mfma_f32_16x16x32_bf16 v[34:37], v[180:183], v[58:61], v[106:109]
	v_mfma_f32_16x16x32_bf16 v[62:65], v[184:187], v[66:69], v[34:37]
	s_waitcnt lgkmcnt(1)
	v_mfma_f32_16x16x32_bf16 v[34:37], v[2:5], v[188:191], v[196:199]
	s_waitcnt lgkmcnt(0)
	v_mfma_f32_16x16x32_bf16 v[42:45], v[6:9], v[200:203], v[34:37]
	v_mfma_f32_16x16x32_bf16 v[34:37], v[180:183], v[188:191], v[98:101]
	v_mfma_f32_16x16x32_bf16 v[34:37], v[184:187], v[200:203], v[34:37]
	s_setprio 0
	s_barrier
	ds_read_b128 v[130:133], v151 offset:49152
	ds_read_b128 v[160:163], v151 offset:50176
	ds_read_b128 v[196:199], v151 offset:51200
	ds_read_b128 v[148:151], v151 offset:52224
	s_waitcnt vmcnt(0)
	s_barrier
	s_waitcnt lgkmcnt(0)
	s_setprio 1
	s_waitcnt lgkmcnt(3)
	v_mfma_f32_16x16x32_bf16 v[98:101], v[130:133], v[18:21], v[222:225]
	s_waitcnt lgkmcnt(1)
	v_mfma_f32_16x16x32_bf16 v[18:21], v[196:199], v[18:21], v[90:93]
	s_waitcnt lgkmcnt(0)
	v_mfma_f32_16x16x32_bf16 v[122:125], v[148:151], v[22:25], v[18:21]
	v_mfma_f32_16x16x32_bf16 v[18:21], v[130:133], v[38:41], v[86:89]
	v_mfma_f32_16x16x32_bf16 v[114:117], v[160:163], v[46:49], v[18:21]
	v_mfma_f32_16x16x32_bf16 v[18:21], v[196:199], v[38:41], v[82:85]
	v_mfma_f32_16x16x32_bf16 v[106:109], v[148:151], v[46:49], v[18:21]
	v_mfma_f32_16x16x32_bf16 v[18:21], v[130:133], v[58:61], v[78:81]
	v_mfma_f32_16x16x32_bf16 v[126:129], v[160:163], v[22:25], v[98:101]
	v_mfma_f32_16x16x32_bf16 v[98:101], v[160:163], v[66:69], v[18:21]
	v_mfma_f32_16x16x32_bf16 v[18:21], v[196:199], v[58:61], v[164:167]
	v_mfma_f32_16x16x32_bf16 v[90:93], v[148:151], v[66:69], v[18:21]
	v_mfma_f32_16x16x32_bf16 v[18:21], v[130:133], v[188:191], v[70:73]
	v_mfma_f32_16x16x32_bf16 v[66:69], v[160:163], v[200:203], v[18:21]
	v_mfma_f32_16x16x32_bf16 v[18:21], v[196:199], v[188:191], v[168:171]
	v_mfma_f32_16x16x32_bf16 v[58:61], v[148:151], v[200:203], v[18:21]
	s_setprio 0
	s_barrier
	ds_read_b128 v[82:85], v0 offset:49152
	ds_read_b128 v[164:167], v0 offset:50176
	ds_read_b128 v[168:171], v0 offset:51200
	ds_read_b128 v[188:191], v0 offset:52224
	ds_read_b128 v[200:203], v0 offset:53248
	ds_read_b128 v[222:225], v0 offset:54272
	ds_read_b128 v[244:247], v0 offset:55296
	ds_read_b128 v[248:251], v0 offset:56320
	s_barrier
	s_waitcnt lgkmcnt(0)
	s_setprio 1
	s_waitcnt lgkmcnt(7)
	v_mfma_f32_16x16x32_bf16 v[18:21], v[2:5], v[82:85], v[192:195]
	s_waitcnt lgkmcnt(6)
	v_mfma_f32_16x16x32_bf16 v[78:81], v[6:9], v[164:167], v[18:21]
	v_mfma_f32_16x16x32_bf16 v[18:21], v[180:183], v[82:85], v[232:235]
	v_mfma_f32_16x16x32_bf16 v[70:73], v[184:187], v[164:167], v[18:21]
	s_waitcnt lgkmcnt(5)
	v_mfma_f32_16x16x32_bf16 v[18:21], v[2:5], v[168:171], v[54:57]
	s_waitcnt lgkmcnt(4)
	v_mfma_f32_16x16x32_bf16 v[46:49], v[6:9], v[188:191], v[18:21]
	v_mfma_f32_16x16x32_bf16 v[18:21], v[180:183], v[168:171], v[50:53]
	v_mfma_f32_16x16x32_bf16 v[38:41], v[184:187], v[188:191], v[18:21]
	s_waitcnt lgkmcnt(3)
	v_mfma_f32_16x16x32_bf16 v[18:21], v[2:5], v[200:203], v[236:239]
	s_waitcnt lgkmcnt(1)
	v_mfma_f32_16x16x32_bf16 v[2:5], v[2:5], v[244:247], v[134:137]
	v_mfma_f32_16x16x32_bf16 v[22:25], v[6:9], v[222:225], v[18:21]
	v_mfma_f32_16x16x32_bf16 v[18:21], v[180:183], v[200:203], v[240:243]
	s_waitcnt lgkmcnt(0)
	v_mfma_f32_16x16x32_bf16 v[6:9], v[6:9], v[248:251], v[2:5]
	v_mfma_f32_16x16x32_bf16 v[2:5], v[180:183], v[244:247], v[138:141]
	v_mfma_f32_16x16x32_bf16 v[18:21], v[184:187], v[222:225], v[18:21]
	v_mfma_f32_16x16x32_bf16 v[2:5], v[184:187], v[248:251], v[2:5]
	s_setprio 0
	s_setprio 1
	v_mfma_f32_16x16x32_bf16 v[26:29], v[196:199], v[82:85], v[26:29]
	v_mfma_f32_16x16x32_bf16 v[30:33], v[130:133], v[82:85], v[30:33]
	v_mfma_f32_16x16x32_bf16 v[82:85], v[148:151], v[164:167], v[26:29]
	v_mfma_f32_16x16x32_bf16 v[26:29], v[130:133], v[168:171], v[152:155]
	v_mfma_f32_16x16x32_bf16 v[54:57], v[160:163], v[188:191], v[26:29]
	v_mfma_f32_16x16x32_bf16 v[26:29], v[196:199], v[168:171], v[156:159]
	v_mfma_f32_16x16x32_bf16 v[10:13], v[196:199], v[200:203], v[10:13]
	v_mfma_f32_16x16x32_bf16 v[50:53], v[148:151], v[188:191], v[26:29]
	v_mfma_f32_16x16x32_bf16 v[14:17], v[130:133], v[200:203], v[14:17]
	v_mfma_f32_16x16x32_bf16 v[26:29], v[148:151], v[222:225], v[10:13]
	v_mfma_f32_16x16x32_bf16 v[10:13], v[130:133], v[244:247], v[172:175]
	v_mfma_f32_16x16x32_bf16 v[86:89], v[160:163], v[164:167], v[30:33]
	v_mfma_f32_16x16x32_bf16 v[30:33], v[160:163], v[222:225], v[14:17]
	v_mfma_f32_16x16x32_bf16 v[14:17], v[160:163], v[248:251], v[10:13]
	v_mfma_f32_16x16x32_bf16 v[10:13], v[196:199], v[244:247], v[176:179]
	v_mfma_f32_16x16x32_bf16 v[10:13], v[148:151], v[248:251], v[10:13]
	s_setprio 0
	s_movk_i32 s0, 0x100
	v_cmp_gt_u32_e32 vcc, s0, v142
	s_barrier
	s_and_saveexec_b64 s[0:1], vcc
	s_cbranch_execz .LBB0_674
	s_barrier
	s_branch .LBB0_674

.LBB0_761:
	ds_read_b128 v[164:167], v148
	ds_read_b128 v[168:171], v148 offset:1024
	ds_read_b128 v[172:175], v148 offset:2048
	ds_read_b128 v[176:179], v148 offset:3072
	v_lshl_add_u64 v[204:205], v[136:137], 0, s[10:11]
	v_lshl_add_u64 v[228:229], v[204:205], 0, s[34:35]
	s_add_i32 m0, s1, 0xc000
	ds_read_b128 v[180:183], v147
	ds_read_b128 v[184:187], v147 offset:1024
	ds_read_b128 v[188:191], v147 offset:2048
	ds_read_b128 v[192:195], v147 offset:3072
	ds_read_b128 v[196:199], v147 offset:4096
	ds_read_b128 v[200:203], v147 offset:5120
	ds_read_b128 v[222:225], v147 offset:6144
	ds_read_b128 v[232:235], v147 offset:7168
	global_load_lds_dwordx4 v[228:229], off
	v_lshl_add_u64 v[210:211], v[138:139], 0, s[10:11]
	s_add_i32 m0, s1, 0xe000
	v_lshl_add_u64 v[152:153], v[210:211], 0, s[34:35]
	global_load_lds_dwordx4 v[152:153], off
	s_barrier
	s_waitcnt lgkmcnt(0)
	v_mfma_f32_16x16x32_bf16 v[126:129], v[164:167], v[180:183], v[126:129]
	v_mfma_f32_16x16x32_bf16 v[122:125], v[172:175], v[180:183], v[122:125]
	v_mfma_f32_16x16x32_bf16 v[118:121], v[164:167], v[188:191], v[118:121]
	v_mfma_f32_16x16x32_bf16 v[114:117], v[172:175], v[188:191], v[114:117]
	v_mfma_f32_16x16x32_bf16 v[110:113], v[164:167], v[196:199], v[110:113]
	v_mfma_f32_16x16x32_bf16 v[106:109], v[172:175], v[196:199], v[106:109]
	v_mfma_f32_16x16x32_bf16 v[102:105], v[164:167], v[222:225], v[102:105]
	v_mfma_f32_16x16x32_bf16 v[98:101], v[172:175], v[222:225], v[98:101]
	v_mfma_f32_16x16x32_bf16 v[126:129], v[168:171], v[184:187], v[126:129]
	v_mfma_f32_16x16x32_bf16 v[122:125], v[176:179], v[184:187], v[122:125]
	v_mfma_f32_16x16x32_bf16 v[118:121], v[168:171], v[192:195], v[118:121]
	v_mfma_f32_16x16x32_bf16 v[114:117], v[176:179], v[192:195], v[114:117]
	v_mfma_f32_16x16x32_bf16 v[110:113], v[168:171], v[200:203], v[110:113]
	v_mfma_f32_16x16x32_bf16 v[106:109], v[176:179], v[200:203], v[106:109]
	v_mfma_f32_16x16x32_bf16 v[102:105], v[168:171], v[232:235], v[102:105]
	v_mfma_f32_16x16x32_bf16 v[98:101], v[176:179], v[232:235], v[98:101]
	s_barrier
	v_lshl_add_u64 v[216:217], v[132:133], 0, s[10:11]
	s_add_i32 m0, s1, 0xff00
	ds_read_b128 v[236:239], v148 offset:16384
	ds_read_b128 v[240:243], v148 offset:17408
	ds_read_b128 v[244:247], v148 offset:18432
	ds_read_b128 v[248:251], v148 offset:19456
	global_load_lds_dwordx4 v[216:217], off offset:256
	s_add_i32 m0, s1, 0x11f00
	v_lshl_add_u64 v[218:219], v[134:135], 0, s[10:11]
	global_load_lds_dwordx4 v[218:219], off offset:256
	s_barrier
	s_waitcnt lgkmcnt(0)
	v_mfma_f32_16x16x32_bf16 v[94:97], v[236:239], v[180:183], v[94:97]
	v_mfma_f32_16x16x32_bf16 v[90:93], v[244:247], v[180:183], v[90:93]
	v_mfma_f32_16x16x32_bf16 v[86:89], v[236:239], v[188:191], v[86:89]
	v_mfma_f32_16x16x32_bf16 v[82:85], v[244:247], v[188:191], v[82:85]
	v_mfma_f32_16x16x32_bf16 v[78:81], v[236:239], v[196:199], v[78:81]
	v_mfma_f32_16x16x32_bf16 v[74:77], v[244:247], v[196:199], v[74:77]
	v_mfma_f32_16x16x32_bf16 v[70:73], v[236:239], v[222:225], v[70:73]
	v_mfma_f32_16x16x32_bf16 v[66:69], v[244:247], v[222:225], v[66:69]
	v_mfma_f32_16x16x32_bf16 v[94:97], v[240:243], v[184:187], v[94:97]
	v_mfma_f32_16x16x32_bf16 v[90:93], v[248:251], v[184:187], v[90:93]
	v_mfma_f32_16x16x32_bf16 v[86:89], v[240:243], v[192:195], v[86:89]
	v_mfma_f32_16x16x32_bf16 v[82:85], v[248:251], v[192:195], v[82:85]
	v_mfma_f32_16x16x32_bf16 v[78:81], v[240:243], v[200:203], v[78:81]
	v_mfma_f32_16x16x32_bf16 v[74:77], v[248:251], v[200:203], v[74:77]
	v_mfma_f32_16x16x32_bf16 v[70:73], v[240:243], v[232:235], v[70:73]
	v_mfma_f32_16x16x32_bf16 v[66:69], v[248:251], v[232:235], v[66:69]
	v_lshl_add_u64 v[158:159], v[204:205], 0, s[74:75]
	s_mov_b32 m0, s1
	s_barrier
	ds_read_b128 v[180:183], v147 offset:16384
	ds_read_b128 v[184:187], v147 offset:17408
	ds_read_b128 v[188:191], v147 offset:18432
	ds_read_b128 v[192:195], v147 offset:19456
	ds_read_b128 v[196:199], v147 offset:20480
	ds_read_b128 v[200:203], v147 offset:21504
	ds_read_b128 v[222:225], v147 offset:22528
	ds_read_b128 v[232:235], v147 offset:23552
	global_load_lds_dwordx4 v[158:159], off
	s_add_i32 m0, s1, 0x1f00
	s_nop 0
	global_load_lds_dwordx4 v[210:211], off offset:256
	s_barrier
	s_waitcnt lgkmcnt(0)
	v_mfma_f32_16x16x32_bf16 v[62:65], v[164:167], v[180:183], v[62:65]
	v_mfma_f32_16x16x32_bf16 v[58:61], v[172:175], v[180:183], v[58:61]
	v_mfma_f32_16x16x32_bf16 v[54:57], v[164:167], v[188:191], v[54:57]
	v_mfma_f32_16x16x32_bf16 v[50:53], v[172:175], v[188:191], v[50:53]
	v_mfma_f32_16x16x32_bf16 v[46:49], v[164:167], v[196:199], v[46:49]
	v_mfma_f32_16x16x32_bf16 v[42:45], v[172:175], v[196:199], v[42:45]
	v_mfma_f32_16x16x32_bf16 v[38:41], v[164:167], v[222:225], v[38:41]
	v_mfma_f32_16x16x32_bf16 v[34:37], v[172:175], v[222:225], v[34:37]
	v_mfma_f32_16x16x32_bf16 v[62:65], v[168:171], v[184:187], v[62:65]
	v_mfma_f32_16x16x32_bf16 v[58:61], v[176:179], v[184:187], v[58:61]
	v_mfma_f32_16x16x32_bf16 v[54:57], v[168:171], v[192:195], v[54:57]
	v_mfma_f32_16x16x32_bf16 v[50:53], v[176:179], v[192:195], v[50:53]
	v_mfma_f32_16x16x32_bf16 v[46:49], v[168:171], v[200:203], v[46:49]
	v_mfma_f32_16x16x32_bf16 v[42:45], v[176:179], v[200:203], v[42:45]
	v_mfma_f32_16x16x32_bf16 v[38:41], v[168:171], v[232:235], v[38:41]
	v_mfma_f32_16x16x32_bf16 v[34:37], v[176:179], v[232:235], v[34:37]
	s_barrier
	s_add_i32 m0, s1, 0x14000
	v_lshl_add_u64 v[154:155], v[216:217], 0, s[78:79]
	global_load_lds_dwordx4 v[154:155], off
	s_add_i32 m0, s1, 0x16000
	v_lshl_add_u64 v[156:157], v[218:219], 0, s[78:79]
	global_load_lds_dwordx4 v[156:157], off
	s_waitcnt vmcnt(6)
	s_barrier
	v_mfma_f32_16x16x32_bf16 v[30:33], v[236:239], v[180:183], v[30:33]
	v_mfma_f32_16x16x32_bf16 v[26:29], v[244:247], v[180:183], v[26:29]
	v_mfma_f32_16x16x32_bf16 v[22:25], v[236:239], v[188:191], v[22:25]
	v_mfma_f32_16x16x32_bf16 v[18:21], v[244:247], v[188:191], v[18:21]
	v_mfma_f32_16x16x32_bf16 v[14:17], v[236:239], v[196:199], v[14:17]
	v_mfma_f32_16x16x32_bf16 v[10:13], v[244:247], v[196:199], v[10:13]
	v_mfma_f32_16x16x32_bf16 v[6:9], v[236:239], v[222:225], v[6:9]
	v_mfma_f32_16x16x32_bf16 v[2:5], v[244:247], v[222:225], v[2:5]
	v_mfma_f32_16x16x32_bf16 v[30:33], v[240:243], v[184:187], v[30:33]
	v_mfma_f32_16x16x32_bf16 v[26:29], v[248:251], v[184:187], v[26:29]
	v_mfma_f32_16x16x32_bf16 v[22:25], v[240:243], v[192:195], v[22:25]
	v_mfma_f32_16x16x32_bf16 v[18:21], v[248:251], v[192:195], v[18:21]
	v_mfma_f32_16x16x32_bf16 v[14:17], v[240:243], v[200:203], v[14:17]
	v_mfma_f32_16x16x32_bf16 v[10:13], v[248:251], v[200:203], v[10:13]
	v_mfma_f32_16x16x32_bf16 v[6:9], v[240:243], v[232:235], v[6:9]
	v_mfma_f32_16x16x32_bf16 v[2:5], v[248:251], v[232:235], v[2:5]
	s_barrier
	ds_read_b128 v[164:167], v148 offset:32768
	ds_read_b128 v[168:171], v148 offset:33792
	ds_read_b128 v[172:175], v148 offset:34816
	ds_read_b128 v[176:179], v148 offset:35840
	s_add_i32 m0, s1, 0x3f80
	ds_read_b128 v[180:183], v147 offset:32768
	ds_read_b128 v[184:187], v147 offset:33792
	ds_read_b128 v[188:191], v147 offset:34816
	ds_read_b128 v[192:195], v147 offset:35840
	ds_read_b128 v[196:199], v147 offset:36864
	ds_read_b128 v[200:203], v147 offset:37888
	ds_read_b128 v[222:225], v147 offset:38912
	ds_read_b128 v[232:235], v147 offset:39936
	global_load_lds_dwordx4 v[228:229], off offset:128
	s_add_i32 m0, s1, 0x5f80
	s_nop 0
	global_load_lds_dwordx4 v[152:153], off offset:128
	s_barrier
	s_waitcnt lgkmcnt(0)
	v_mfma_f32_16x16x32_bf16 v[126:129], v[164:167], v[180:183], v[126:129]
	v_mfma_f32_16x16x32_bf16 v[122:125], v[172:175], v[180:183], v[122:125]
	v_mfma_f32_16x16x32_bf16 v[118:121], v[164:167], v[188:191], v[118:121]
	v_mfma_f32_16x16x32_bf16 v[114:117], v[172:175], v[188:191], v[114:117]
	v_mfma_f32_16x16x32_bf16 v[110:113], v[164:167], v[196:199], v[110:113]
	v_mfma_f32_16x16x32_bf16 v[106:109], v[172:175], v[196:199], v[106:109]
	v_mfma_f32_16x16x32_bf16 v[102:105], v[164:167], v[222:225], v[102:105]
	v_mfma_f32_16x16x32_bf16 v[98:101], v[172:175], v[222:225], v[98:101]
	v_mfma_f32_16x16x32_bf16 v[126:129], v[168:171], v[184:187], v[126:129]
	v_mfma_f32_16x16x32_bf16 v[122:125], v[176:179], v[184:187], v[122:125]
	v_mfma_f32_16x16x32_bf16 v[118:121], v[168:171], v[192:195], v[118:121]
	v_mfma_f32_16x16x32_bf16 v[114:117], v[176:179], v[192:195], v[114:117]
	v_mfma_f32_16x16x32_bf16 v[110:113], v[168:171], v[200:203], v[110:113]
	v_mfma_f32_16x16x32_bf16 v[106:109], v[176:179], v[200:203], v[106:109]
	v_mfma_f32_16x16x32_bf16 v[102:105], v[168:171], v[232:235], v[102:105]
	v_mfma_f32_16x16x32_bf16 v[98:101], v[176:179], v[232:235], v[98:101]
	s_barrier
	s_add_i32 m0, s1, 0x17e80
	ds_read_b128 v[236:239], v148 offset:49152
	ds_read_b128 v[240:243], v148 offset:50176
	ds_read_b128 v[244:247], v148 offset:51200
	ds_read_b128 v[248:251], v148 offset:52224
	global_load_lds_dwordx4 v[216:217], off offset:384
	s_add_i32 m0, s1, 0x19e80
	s_nop 0
	global_load_lds_dwordx4 v[218:219], off offset:384
	s_barrier
	s_waitcnt lgkmcnt(0)
	v_mfma_f32_16x16x32_bf16 v[94:97], v[236:239], v[180:183], v[94:97]
	v_mfma_f32_16x16x32_bf16 v[90:93], v[244:247], v[180:183], v[90:93]
	v_mfma_f32_16x16x32_bf16 v[86:89], v[236:239], v[188:191], v[86:89]
	v_mfma_f32_16x16x32_bf16 v[82:85], v[244:247], v[188:191], v[82:85]
	v_mfma_f32_16x16x32_bf16 v[78:81], v[236:239], v[196:199], v[78:81]
	v_mfma_f32_16x16x32_bf16 v[74:77], v[244:247], v[196:199], v[74:77]
	v_mfma_f32_16x16x32_bf16 v[70:73], v[236:239], v[222:225], v[70:73]
	v_mfma_f32_16x16x32_bf16 v[66:69], v[244:247], v[222:225], v[66:69]
	v_mfma_f32_16x16x32_bf16 v[94:97], v[240:243], v[184:187], v[94:97]
	v_mfma_f32_16x16x32_bf16 v[90:93], v[248:251], v[184:187], v[90:93]
	v_mfma_f32_16x16x32_bf16 v[86:89], v[240:243], v[192:195], v[86:89]
	v_mfma_f32_16x16x32_bf16 v[82:85], v[248:251], v[192:195], v[82:85]
	v_mfma_f32_16x16x32_bf16 v[78:81], v[240:243], v[200:203], v[78:81]
	v_mfma_f32_16x16x32_bf16 v[74:77], v[248:251], v[200:203], v[74:77]
	v_mfma_f32_16x16x32_bf16 v[70:73], v[240:243], v[232:235], v[70:73]
	v_mfma_f32_16x16x32_bf16 v[66:69], v[248:251], v[232:235], v[66:69]
	s_add_i32 m0, s1, 0x7e80
	s_barrier
	ds_read_b128 v[180:183], v147 offset:49152
	ds_read_b128 v[184:187], v147 offset:50176
	ds_read_b128 v[188:191], v147 offset:51200
	ds_read_b128 v[192:195], v147 offset:52224
	ds_read_b128 v[196:199], v147 offset:53248
	ds_read_b128 v[200:203], v147 offset:54272
	ds_read_b128 v[222:225], v147 offset:55296
	ds_read_b128 v[232:235], v147 offset:56320
	global_load_lds_dwordx4 v[204:205], off offset:384
	s_add_i32 m0, s1, 0x9e80
	s_nop 0
	global_load_lds_dwordx4 v[210:211], off offset:384
	s_barrier
	s_waitcnt lgkmcnt(0)
	v_mfma_f32_16x16x32_bf16 v[62:65], v[164:167], v[180:183], v[62:65]
	v_mfma_f32_16x16x32_bf16 v[58:61], v[172:175], v[180:183], v[58:61]
	v_mfma_f32_16x16x32_bf16 v[54:57], v[164:167], v[188:191], v[54:57]
	v_mfma_f32_16x16x32_bf16 v[50:53], v[172:175], v[188:191], v[50:53]
	v_mfma_f32_16x16x32_bf16 v[46:49], v[164:167], v[196:199], v[46:49]
	v_mfma_f32_16x16x32_bf16 v[42:45], v[172:175], v[196:199], v[42:45]
	v_mfma_f32_16x16x32_bf16 v[38:41], v[164:167], v[222:225], v[38:41]
	v_mfma_f32_16x16x32_bf16 v[34:37], v[172:175], v[222:225], v[34:37]
	v_mfma_f32_16x16x32_bf16 v[62:65], v[168:171], v[184:187], v[62:65]
	v_mfma_f32_16x16x32_bf16 v[58:61], v[176:179], v[184:187], v[58:61]
	v_mfma_f32_16x16x32_bf16 v[54:57], v[168:171], v[192:195], v[54:57]
	v_mfma_f32_16x16x32_bf16 v[50:53], v[176:179], v[192:195], v[50:53]
	v_mfma_f32_16x16x32_bf16 v[46:49], v[168:171], v[200:203], v[46:49]
	v_mfma_f32_16x16x32_bf16 v[42:45], v[176:179], v[200:203], v[42:45]
	v_mfma_f32_16x16x32_bf16 v[38:41], v[168:171], v[232:235], v[38:41]
	v_mfma_f32_16x16x32_bf16 v[34:37], v[176:179], v[232:235], v[34:37]
	s_barrier
	s_add_i32 m0, s1, 0x1bf80
	s_nop 0
	global_load_lds_dwordx4 v[154:155], off offset:128
	s_add_i32 m0, s1, 0x1df80
	s_nop 0
	global_load_lds_dwordx4 v[156:157], off offset:128
	s_waitcnt vmcnt(6)
	s_barrier
	v_mfma_f32_16x16x32_bf16 v[30:33], v[236:239], v[180:183], v[30:33]
	v_mfma_f32_16x16x32_bf16 v[26:29], v[244:247], v[180:183], v[26:29]
	v_mfma_f32_16x16x32_bf16 v[22:25], v[236:239], v[188:191], v[22:25]
	v_mfma_f32_16x16x32_bf16 v[18:21], v[244:247], v[188:191], v[18:21]
	v_mfma_f32_16x16x32_bf16 v[14:17], v[236:239], v[196:199], v[14:17]
	v_mfma_f32_16x16x32_bf16 v[10:13], v[244:247], v[196:199], v[10:13]
	v_mfma_f32_16x16x32_bf16 v[6:9], v[236:239], v[222:225], v[6:9]
	v_mfma_f32_16x16x32_bf16 v[2:5], v[244:247], v[222:225], v[2:5]
	v_mfma_f32_16x16x32_bf16 v[30:33], v[240:243], v[184:187], v[30:33]
	v_mfma_f32_16x16x32_bf16 v[26:29], v[248:251], v[184:187], v[26:29]
	v_mfma_f32_16x16x32_bf16 v[22:25], v[240:243], v[192:195], v[22:25]
	v_mfma_f32_16x16x32_bf16 v[18:21], v[248:251], v[192:195], v[18:21]
	v_mfma_f32_16x16x32_bf16 v[14:17], v[240:243], v[200:203], v[14:17]
	v_mfma_f32_16x16x32_bf16 v[10:13], v[248:251], v[200:203], v[10:13]
	v_mfma_f32_16x16x32_bf16 v[6:9], v[240:243], v[232:235], v[6:9]
	v_mfma_f32_16x16x32_bf16 v[2:5], v[248:251], v[232:235], v[2:5]
	s_add_i32 s0, s0, 2
	s_add_u32 s10, s10, 0x100
	s_addc_u32 s11, s11, 0
	s_cmpk_lt_u32 s0, 0x54
	s_barrier
	s_cbranch_scc1 .LBB0_761
	s_add_i32 s1, s1, 0x1e000
	s_add_u32 s0, s8, 0x162b80
	s_addc_u32 s1, s9, 0
	v_readfirstlane_b32 s8, v161
	v_lshl_add_u64 v[158:159], s[0:1], 0, v[0:1]
	s_mov_b32 m0, s8
	v_lshl_add_u64 v[130:131], s[0:1], 0, v[130:131]
	v_readfirstlane_b32 s0, v162
	ds_read_b128 v[132:135], v148
	ds_read_b128 v[136:139], v148 offset:1024
	ds_read_b128 v[150:153], v148 offset:2048
	ds_read_b128 v[154:157], v148 offset:3072
	ds_read_b128 v[164:167], v147
	ds_read_b128 v[168:171], v147 offset:1024
	ds_read_b128 v[172:175], v147 offset:2048
	ds_read_b128 v[176:179], v147 offset:3072
	ds_read_b128 v[180:183], v147 offset:4096
	ds_read_b128 v[184:187], v147 offset:5120
	ds_read_b128 v[188:191], v147 offset:6144
	ds_read_b128 v[192:195], v147 offset:7168
	global_load_lds_dwordx4 v[158:159], off
	s_mov_b32 m0, s0
	s_nop 0
	global_load_lds_dwordx4 v[130:131], off
	s_barrier
	s_waitcnt lgkmcnt(0)
	s_setprio 1
	s_waitcnt lgkmcnt(0)
	v_mfma_f32_16x16x32_bf16 v[122:125], v[150:153], v[164:167], v[122:125]
	v_mfma_f32_16x16x32_bf16 v[118:121], v[132:135], v[172:175], v[118:121]
	v_mfma_f32_16x16x32_bf16 v[114:117], v[150:153], v[172:175], v[114:117]
	v_mfma_f32_16x16x32_bf16 v[102:105], v[132:135], v[188:191], v[102:105]
	v_mfma_f32_16x16x32_bf16 v[98:101], v[150:153], v[188:191], v[98:101]
	v_mfma_f32_16x16x32_bf16 v[126:129], v[132:135], v[164:167], v[126:129]
	v_mfma_f32_16x16x32_bf16 v[122:125], v[154:157], v[168:171], v[122:125]
	v_mfma_f32_16x16x32_bf16 v[118:121], v[136:139], v[176:179], v[118:121]
	v_mfma_f32_16x16x32_bf16 v[114:117], v[154:157], v[176:179], v[114:117]
	v_mfma_f32_16x16x32_bf16 v[110:113], v[132:135], v[180:183], v[110:113]
	v_mfma_f32_16x16x32_bf16 v[106:109], v[150:153], v[180:183], v[106:109]
	v_mfma_f32_16x16x32_bf16 v[102:105], v[136:139], v[192:195], v[102:105]
	v_mfma_f32_16x16x32_bf16 v[98:101], v[154:157], v[192:195], v[98:101]
	v_mfma_f32_16x16x32_bf16 v[126:129], v[136:139], v[168:171], v[126:129]
	v_mfma_f32_16x16x32_bf16 v[158:161], v[136:139], v[184:187], v[110:113]
	v_mfma_f32_16x16x32_bf16 v[196:199], v[154:157], v[184:187], v[106:109]
	s_setprio 0
	s_barrier
	ds_read_b128 v[106:109], v148 offset:16384
	ds_read_b128 v[110:113], v148 offset:17408
	ds_read_b128 v[200:203], v148 offset:18432
	ds_read_b128 v[222:225], v148 offset:19456
	s_barrier
	s_waitcnt lgkmcnt(0)
	s_setprio 1
	s_waitcnt lgkmcnt(3)
	v_mfma_f32_16x16x32_bf16 v[86:89], v[106:109], v[172:175], v[86:89]
	s_waitcnt lgkmcnt(1)
	v_mfma_f32_16x16x32_bf16 v[82:85], v[200:203], v[172:175], v[82:85]
	v_mfma_f32_16x16x32_bf16 v[70:73], v[106:109], v[188:191], v[70:73]
	v_mfma_f32_16x16x32_bf16 v[66:69], v[200:203], v[188:191], v[66:69]
	v_mfma_f32_16x16x32_bf16 v[94:97], v[106:109], v[164:167], v[94:97]
	v_mfma_f32_16x16x32_bf16 v[90:93], v[200:203], v[164:167], v[90:93]
	v_mfma_f32_16x16x32_bf16 v[86:89], v[110:113], v[176:179], v[86:89]
	s_waitcnt lgkmcnt(0)
	v_mfma_f32_16x16x32_bf16 v[82:85], v[222:225], v[176:179], v[82:85]
	v_mfma_f32_16x16x32_bf16 v[78:81], v[106:109], v[180:183], v[78:81]
	v_mfma_f32_16x16x32_bf16 v[74:77], v[200:203], v[180:183], v[74:77]
	v_mfma_f32_16x16x32_bf16 v[70:73], v[110:113], v[192:195], v[70:73]
	v_mfma_f32_16x16x32_bf16 v[66:69], v[222:225], v[192:195], v[66:69]
	v_mfma_f32_16x16x32_bf16 v[232:235], v[110:113], v[168:171], v[94:97]
	v_mfma_f32_16x16x32_bf16 v[162:165], v[222:225], v[168:171], v[90:93]
	v_mfma_f32_16x16x32_bf16 v[166:169], v[110:113], v[184:187], v[78:81]
	v_mfma_f32_16x16x32_bf16 v[170:173], v[222:225], v[184:187], v[74:77]
	s_setprio 0
	s_barrier
	s_nop 0
	ds_read_b128 v[74:77], v147 offset:16384
	ds_read_b128 v[78:81], v147 offset:17408
	ds_read_b128 v[90:93], v147 offset:18432
	ds_read_b128 v[94:97], v147 offset:19456
	ds_read_b128 v[174:177], v147 offset:20480
	ds_read_b128 v[178:181], v147 offset:21504
	ds_read_b128 v[182:185], v147 offset:22528
	ds_read_b128 v[186:189], v147 offset:23552
	s_waitcnt vmcnt(4)
	s_barrier
	s_waitcnt lgkmcnt(0)
	s_setprio 1
	s_waitcnt lgkmcnt(7)
	v_mfma_f32_16x16x32_bf16 v[62:65], v[132:135], v[74:77], v[62:65]
	v_mfma_f32_16x16x32_bf16 v[58:61], v[150:153], v[74:77], v[58:61]
	s_waitcnt lgkmcnt(5)
	v_mfma_f32_16x16x32_bf16 v[54:57], v[132:135], v[90:93], v[54:57]
	v_mfma_f32_16x16x32_bf16 v[50:53], v[150:153], v[90:93], v[50:53]
	s_waitcnt lgkmcnt(1)
	v_mfma_f32_16x16x32_bf16 v[38:41], v[132:135], v[182:185], v[38:41]
	v_mfma_f32_16x16x32_bf16 v[34:37], v[150:153], v[182:185], v[34:37]
	v_mfma_f32_16x16x32_bf16 v[62:65], v[136:139], v[78:81], v[62:65]
	v_mfma_f32_16x16x32_bf16 v[58:61], v[154:157], v[78:81], v[58:61]
	v_mfma_f32_16x16x32_bf16 v[54:57], v[136:139], v[94:97], v[54:57]
	v_mfma_f32_16x16x32_bf16 v[50:53], v[154:157], v[94:97], v[50:53]
	v_mfma_f32_16x16x32_bf16 v[46:49], v[132:135], v[174:177], v[46:49]
	v_mfma_f32_16x16x32_bf16 v[42:45], v[150:153], v[174:177], v[42:45]
	s_waitcnt lgkmcnt(0)
	v_mfma_f32_16x16x32_bf16 v[38:41], v[136:139], v[186:189], v[38:41]
	v_mfma_f32_16x16x32_bf16 v[34:37], v[154:157], v[186:189], v[34:37]
	v_mfma_f32_16x16x32_bf16 v[190:193], v[136:139], v[178:181], v[46:49]
	v_mfma_f32_16x16x32_bf16 v[236:239], v[154:157], v[178:181], v[42:45]
	s_setprio 0
	s_setprio 1
	v_mfma_f32_16x16x32_bf16 v[22:25], v[106:109], v[90:93], v[22:25]
	v_mfma_f32_16x16x32_bf16 v[18:21], v[200:203], v[90:93], v[18:21]
	v_mfma_f32_16x16x32_bf16 v[6:9], v[106:109], v[182:185], v[6:9]
	v_mfma_f32_16x16x32_bf16 v[2:5], v[200:203], v[182:185], v[2:5]
	v_mfma_f32_16x16x32_bf16 v[30:33], v[106:109], v[74:77], v[30:33]
	v_mfma_f32_16x16x32_bf16 v[26:29], v[200:203], v[74:77], v[26:29]
	v_mfma_f32_16x16x32_bf16 v[22:25], v[110:113], v[94:97], v[22:25]
	v_mfma_f32_16x16x32_bf16 v[18:21], v[222:225], v[94:97], v[18:21]
	v_mfma_f32_16x16x32_bf16 v[14:17], v[106:109], v[174:177], v[14:17]
	v_mfma_f32_16x16x32_bf16 v[10:13], v[200:203], v[174:177], v[10:13]
	v_mfma_f32_16x16x32_bf16 v[6:9], v[110:113], v[186:189], v[6:9]
	v_mfma_f32_16x16x32_bf16 v[2:5], v[222:225], v[186:189], v[2:5]
	v_mfma_f32_16x16x32_bf16 v[134:137], v[110:113], v[78:81], v[30:33]
	v_mfma_f32_16x16x32_bf16 v[150:153], v[222:225], v[78:81], v[26:29]
	v_mfma_f32_16x16x32_bf16 v[154:157], v[110:113], v[178:181], v[14:17]
	v_mfma_f32_16x16x32_bf16 v[174:177], v[222:225], v[178:181], v[10:13]
	s_setprio 0
	s_barrier
	s_nop 0
	ds_read_b128 v[10:13], v148 offset:32768
	ds_read_b128 v[14:17], v148 offset:33792
	ds_read_b128 v[178:181], v148 offset:34816
	ds_read_b128 v[182:185], v148 offset:35840
	ds_read_b128 v[26:29], v147 offset:32768
	ds_read_b128 v[30:33], v147 offset:33792
	ds_read_b128 v[42:45], v147 offset:34816
	ds_read_b128 v[46:49], v147 offset:35840
	ds_read_b128 v[186:189], v147 offset:36864
	ds_read_b128 v[200:203], v147 offset:37888
	ds_read_b128 v[222:225], v147 offset:38912
	ds_read_b128 v[240:243], v147 offset:39936
	s_waitcnt vmcnt(2)
	s_barrier
	s_waitcnt lgkmcnt(0)
	s_setprio 1
	s_waitcnt lgkmcnt(7)
	v_mfma_f32_16x16x32_bf16 v[74:77], v[10:13], v[26:29], v[126:129]
	s_waitcnt lgkmcnt(6)
	v_mfma_f32_16x16x32_bf16 v[130:133], v[14:17], v[30:33], v[74:77]
	v_mfma_f32_16x16x32_bf16 v[74:77], v[178:181], v[26:29], v[122:125]
	v_mfma_f32_16x16x32_bf16 v[122:125], v[182:185], v[30:33], v[74:77]
	s_waitcnt lgkmcnt(5)
	v_mfma_f32_16x16x32_bf16 v[74:77], v[10:13], v[42:45], v[118:121]
	s_waitcnt lgkmcnt(4)
	v_mfma_f32_16x16x32_bf16 v[110:113], v[14:17], v[46:49], v[74:77]
	v_mfma_f32_16x16x32_bf16 v[74:77], v[178:181], v[42:45], v[114:117]
	v_mfma_f32_16x16x32_bf16 v[106:109], v[182:185], v[46:49], v[74:77]
	s_waitcnt lgkmcnt(3)
	v_mfma_f32_16x16x32_bf16 v[74:77], v[10:13], v[186:189], v[158:161]
	s_waitcnt lgkmcnt(2)
	v_mfma_f32_16x16x32_bf16 v[94:97], v[14:17], v[200:203], v[74:77]
	v_mfma_f32_16x16x32_bf16 v[74:77], v[178:181], v[186:189], v[196:199]
	v_mfma_f32_16x16x32_bf16 v[90:93], v[182:185], v[200:203], v[74:77]
	s_waitcnt lgkmcnt(1)
	v_mfma_f32_16x16x32_bf16 v[74:77], v[10:13], v[222:225], v[102:105]
	s_waitcnt lgkmcnt(0)
	v_mfma_f32_16x16x32_bf16 v[78:81], v[14:17], v[240:243], v[74:77]
	v_mfma_f32_16x16x32_bf16 v[74:77], v[178:181], v[222:225], v[98:101]
	v_mfma_f32_16x16x32_bf16 v[74:77], v[182:185], v[240:243], v[74:77]
	s_setprio 0
	s_barrier
	ds_read_b128 v[126:129], v148 offset:49152
	ds_read_b128 v[158:161], v148 offset:50176
	ds_read_b128 v[194:197], v148 offset:51200
	ds_read_b128 v[244:247], v148 offset:52224
	s_waitcnt vmcnt(0)
	s_barrier
	s_waitcnt lgkmcnt(0)
	s_setprio 1
	s_waitcnt lgkmcnt(3)
	v_mfma_f32_16x16x32_bf16 v[98:101], v[126:129], v[26:29], v[232:235]
	s_waitcnt lgkmcnt(1)
	v_mfma_f32_16x16x32_bf16 v[26:29], v[194:197], v[26:29], v[162:165]
	s_waitcnt lgkmcnt(0)
	v_mfma_f32_16x16x32_bf16 v[114:117], v[244:247], v[30:33], v[26:29]
	v_mfma_f32_16x16x32_bf16 v[26:29], v[126:129], v[42:45], v[86:89]
	v_mfma_f32_16x16x32_bf16 v[102:105], v[158:161], v[46:49], v[26:29]
	v_mfma_f32_16x16x32_bf16 v[26:29], v[194:197], v[42:45], v[82:85]
	v_mfma_f32_16x16x32_bf16 v[118:121], v[158:161], v[30:33], v[98:101]
	v_mfma_f32_16x16x32_bf16 v[98:101], v[244:247], v[46:49], v[26:29]
	v_mfma_f32_16x16x32_bf16 v[26:29], v[126:129], v[186:189], v[166:169]
	v_mfma_f32_16x16x32_bf16 v[86:89], v[158:161], v[200:203], v[26:29]
	v_mfma_f32_16x16x32_bf16 v[26:29], v[194:197], v[186:189], v[170:173]
	v_mfma_f32_16x16x32_bf16 v[82:85], v[244:247], v[200:203], v[26:29]
	v_mfma_f32_16x16x32_bf16 v[26:29], v[126:129], v[222:225], v[70:73]
	v_mfma_f32_16x16x32_bf16 v[70:73], v[158:161], v[240:243], v[26:29]
	v_mfma_f32_16x16x32_bf16 v[26:29], v[194:197], v[222:225], v[66:69]
	v_mfma_f32_16x16x32_bf16 v[66:69], v[244:247], v[240:243], v[26:29]
	s_setprio 0
	s_barrier
	ds_read_b128 v[162:165], v147 offset:49152
	ds_read_b128 v[166:169], v147 offset:50176
	ds_read_b128 v[170:173], v147 offset:51200
	ds_read_b128 v[186:189], v147 offset:52224
	ds_read_b128 v[198:201], v147 offset:53248
	ds_read_b128 v[202:205], v147 offset:54272
	ds_read_b128 v[222:225], v147 offset:55296
	ds_read_b128 v[146:149], v147 offset:56320
	s_barrier
	s_waitcnt lgkmcnt(0)
	s_setprio 1
	s_waitcnt lgkmcnt(7)
	v_mfma_f32_16x16x32_bf16 v[26:29], v[10:13], v[162:165], v[62:65]
	s_waitcnt lgkmcnt(6)
	v_mfma_f32_16x16x32_bf16 v[62:65], v[14:17], v[166:169], v[26:29]
	v_mfma_f32_16x16x32_bf16 v[26:29], v[178:181], v[162:165], v[58:61]
	v_mfma_f32_16x16x32_bf16 v[58:61], v[182:185], v[166:169], v[26:29]
	s_waitcnt lgkmcnt(5)
	v_mfma_f32_16x16x32_bf16 v[26:29], v[10:13], v[170:173], v[54:57]
	s_waitcnt lgkmcnt(4)
	v_mfma_f32_16x16x32_bf16 v[46:49], v[14:17], v[186:189], v[26:29]
	v_mfma_f32_16x16x32_bf16 v[26:29], v[178:181], v[170:173], v[50:53]
	v_mfma_f32_16x16x32_bf16 v[42:45], v[182:185], v[186:189], v[26:29]
	s_waitcnt lgkmcnt(3)
	v_mfma_f32_16x16x32_bf16 v[26:29], v[10:13], v[198:201], v[190:193]
	s_waitcnt lgkmcnt(1)
	v_mfma_f32_16x16x32_bf16 v[10:13], v[10:13], v[222:225], v[38:41]
	v_mfma_f32_16x16x32_bf16 v[30:33], v[14:17], v[202:205], v[26:29]
	v_mfma_f32_16x16x32_bf16 v[26:29], v[178:181], v[198:201], v[236:239]
	s_waitcnt lgkmcnt(0)
	v_mfma_f32_16x16x32_bf16 v[14:17], v[14:17], v[146:149], v[10:13]
	v_mfma_f32_16x16x32_bf16 v[10:13], v[178:181], v[222:225], v[34:37]
	v_mfma_f32_16x16x32_bf16 v[26:29], v[182:185], v[202:205], v[26:29]
	v_mfma_f32_16x16x32_bf16 v[10:13], v[182:185], v[146:149], v[10:13]
	s_setprio 0
	s_setprio 1
	v_mfma_f32_16x16x32_bf16 v[34:37], v[126:129], v[162:165], v[134:137]
	v_mfma_f32_16x16x32_bf16 v[54:57], v[158:161], v[166:169], v[34:37]
	v_mfma_f32_16x16x32_bf16 v[34:37], v[194:197], v[162:165], v[150:153]
	v_mfma_f32_16x16x32_bf16 v[18:21], v[194:197], v[170:173], v[18:21]
	v_mfma_f32_16x16x32_bf16 v[50:53], v[244:247], v[166:169], v[34:37]
	v_mfma_f32_16x16x32_bf16 v[22:25], v[126:129], v[170:173], v[22:25]
	v_mfma_f32_16x16x32_bf16 v[34:37], v[244:247], v[186:189], v[18:21]
	v_mfma_f32_16x16x32_bf16 v[18:21], v[126:129], v[198:201], v[154:157]
	v_mfma_f32_16x16x32_bf16 v[38:41], v[158:161], v[186:189], v[22:25]
	v_mfma_f32_16x16x32_bf16 v[22:25], v[158:161], v[202:205], v[18:21]
	v_mfma_f32_16x16x32_bf16 v[18:21], v[194:197], v[198:201], v[174:177]
	v_mfma_f32_16x16x32_bf16 v[6:9], v[126:129], v[222:225], v[6:9]
	v_mfma_f32_16x16x32_bf16 v[2:5], v[194:197], v[222:225], v[2:5]
	v_mfma_f32_16x16x32_bf16 v[18:21], v[244:247], v[202:205], v[18:21]
	v_mfma_f32_16x16x32_bf16 v[6:9], v[158:161], v[146:149], v[6:9]
	v_mfma_f32_16x16x32_bf16 v[2:5], v[244:247], v[146:149], v[2:5]
	s_setprio 0
	s_movk_i32 s0, 0x100
	v_cmp_gt_u32_e32 vcc, s0, v140
	s_barrier
	s_and_saveexec_b64 s[0:1], vcc
	s_cbranch_execz .LBB0_764
	s_barrier
